# UQ epilogue: rotary cos/sin table loads requested one row block ahead into a spare register set (only row blocks 0 and 4 wait a full round trip)
# speedup vs baseline: 1.0066x; 1.0063x over previous
; #define PG8_STAGE(bufoff, gbase, voff) do { _Pragma("unroll") for (int _i = 0; _i < 2; ++_i) \
;     __builtin_amdgcn_global_load_lds((const unsigned*)((const char*)(gbase) + (voff)[_i]), (LAS unsigned*)(lds + (bufoff) + ldsw + _i * 8192), 16, 0, 0); } while (0)
; #define PG8_LDA(dst, b, h) do { _Pragma("unroll") for (int m = 0; m < 4; ++m) _Pragma("unroll") for (int k = 0; k < 2; ++k) dst[m][k] = *(const LAS bf16x8*)(lds + PG8_SA(b, h) + aoff + m * 2048 + k * 1024); } while (0)
; #define PG8_LDB(dst, b, h) do { _Pragma("unroll") for (int n = 0; n < 2; ++n) _Pragma("unroll") for (int k = 0; k < 2; ++k) dst[n][k] = *(const LAS bf16x8*)(lds + PG8_SB(b, h) + boff + n * 2048 + k * 1024); } while (0)
; #define PG8_MMA(ai, bj, At, Bt) do { __builtin_amdgcn_s_setprio(1); _Pragma("unroll") for (int m = 0; m < 4; ++m) _Pragma("unroll") for (int n = 0; n < 2; ++n) _Pragma("unroll") for (int k = 0; k < 2; ++k) \
;     acc[ai][bj][m][n] = __builtin_amdgcn_mfma_f32_16x16x32_bf16(Bt[n][k], At[m][k], acc[ai][bj][m][n], 0, 0, 0); __builtin_amdgcn_s_setprio(0); } while (0)
; #define PG8_WAIT_V(n) asm volatile("s_waitcnt vmcnt(" #n ")" ::: "memory")
; #define PG8_WAIT_L(n) asm volatile("s_waitcnt lgkmcnt(" #n ")" ::: "memory")
; #define PG8_BAR __builtin_amdgcn_s_barrier()
; #define PG8_SCHED __builtin_amdgcn_sched_barrier(0)
; template <class Epi, class Sched>
; DI void gemm_phase(LAS unsigned char* lds, const Gemm g, const Sched& S, const Epi& E) {
;     ...
;     for (int t = 0; t < nt; t += 2) {
;       const bool last = (t == nt - 2);
;       const char* a1 = cA + (size_t)(t + 1) * kstep;
;       const char* a2 = last ? nA : cA + (size_t)(t + 2) * kstep; const char* b2 = last ? nB : cB + (size_t)(t + 2) * kstep;
;       const char* a3 = a2 + kstep; const char* b3 = b2 + kstep;
;       PG8_LDB(B0, 0, 0); PG8_SCHED; PG8_LDA(At, 0, 0); PG8_STAGE(PG8_SA(1, 1), a1 + hstep, voffA);
;       PG8_WAIT_L(8); PG8_BAR; PG8_WAIT_L(0); PG8_MMA(0, 0, At, B0); PG8_BAR; PG8_SCHED;
;       PG8_LDB(B1, 0, 1); PG8_STAGE(PG8_SB(0, 0), b2, voffB);
;       PG8_BAR; PG8_WAIT_L(0); PG8_MMA(0, 1, At, B1); PG8_BAR;
;       PG8_LDA(At, 0, 1); PG8_STAGE(PG8_SA(0, 0), a2, voffA);
;       PG8_BAR; PG8_WAIT_L(0); PG8_MMA(1, 0, At, B0); PG8_BAR; PG8_SCHED;
;       PG8_STAGE(PG8_SB(0, 1), b2 + hstep, voffB);
;       PG8_WAIT_V(6); PG8_BAR; PG8_MMA(1, 1, At, B1); PG8_BAR;
.LBB0_1202:
	s_add_u32 s20, s18, 0x100
	s_addc_u32 s21, s19, 0
	s_add_i32 s55, 0, 0x10000
	ds_read_b128 v[140:143], v224
	ds_read_b128 v[146:149], v224 offset:1024
	ds_read_b128 v[150:153], v224 offset:2048
	ds_read_b128 v[154:157], v224 offset:3072
	s_cmp_eq_u32 s54, 2
	s_cselect_b32 s29, s3, s21
	s_cselect_b32 s28, s2, s20
	s_cselect_b32 s23, s5, s53
	s_cselect_b32 s22, s4, s52
	s_add_i32 m0, s38, 0xc000
	ds_read_b128 v[158:161], v163
	ds_read_b128 v[164:167], v163 offset:1024
	ds_read_b128 v[168:171], v163 offset:2048
	ds_read_b128 v[172:175], v163 offset:3072
	ds_read_b128 v[176:179], v163 offset:4096
	ds_read_b128 v[196:199], v163 offset:5120
	ds_read_b128 v[200:203], v163 offset:6144
	ds_read_b128 v[204:207], v163 offset:7168
	global_load_lds_dwordx4 v136, s[18:19]
	s_add_i32 m0, s38, 0xe000
	s_nop 0
	global_load_lds_dwordx4 v138, s[18:19]
	s_waitcnt lgkmcnt(8)
	s_barrier
	s_waitcnt lgkmcnt(0)
	v_mfma_f32_16x16x32_bf16 v[124:127], v[140:143], v[158:161], v[124:127]
	v_mfma_f32_16x16x32_bf16 v[120:123], v[150:153], v[158:161], v[120:123]
	v_mfma_f32_16x16x32_bf16 v[108:111], v[140:143], v[168:171], v[108:111]
	v_mfma_f32_16x16x32_bf16 v[104:107], v[150:153], v[168:171], v[104:107]
	v_mfma_f32_16x16x32_bf16 v[92:95], v[140:143], v[176:179], v[92:95]
	v_mfma_f32_16x16x32_bf16 v[88:91], v[150:153], v[176:179], v[88:91]
	v_mfma_f32_16x16x32_bf16 v[76:79], v[140:143], v[200:203], v[76:79]
	v_mfma_f32_16x16x32_bf16 v[72:75], v[150:153], v[200:203], v[72:75]
	v_mfma_f32_16x16x32_bf16 v[124:127], v[146:149], v[164:167], v[124:127]
	v_mfma_f32_16x16x32_bf16 v[120:123], v[154:157], v[164:167], v[120:123]
	v_mfma_f32_16x16x32_bf16 v[108:111], v[146:149], v[172:175], v[108:111]
	v_mfma_f32_16x16x32_bf16 v[104:107], v[154:157], v[172:175], v[104:107]
	v_mfma_f32_16x16x32_bf16 v[92:95], v[146:149], v[196:199], v[92:95]
	v_mfma_f32_16x16x32_bf16 v[88:91], v[154:157], v[196:199], v[88:91]
	v_mfma_f32_16x16x32_bf16 v[76:79], v[146:149], v[204:207], v[76:79]
	v_mfma_f32_16x16x32_bf16 v[72:75], v[154:157], v[204:207], v[72:75]
	s_barrier
	s_add_i32 s56, 0, 0x14000
	s_add_i32 s18, s55, s35
	s_add_u32 vcc_lo, s22, s0
	s_addc_u32 vcc_hi, s23, s1
	s_mov_b32 m0, s18
	ds_read_b128 v[208:211], v225
	ds_read_b128 v[212:215], v225 offset:1024
	ds_read_b128 v[216:219], v225 offset:2048
	ds_read_b128 v[220:223], v225 offset:3072
	global_load_lds_dwordx4 v130, s[22:23]
	s_add_i32 m0, s18, 0x2000
	s_nop 0
	global_load_lds_dwordx4 v134, s[22:23]
	s_barrier
	s_waitcnt lgkmcnt(0)
	v_mfma_f32_16x16x32_bf16 v[116:119], v[208:211], v[158:161], v[116:119]
	v_mfma_f32_16x16x32_bf16 v[112:115], v[216:219], v[158:161], v[112:115]
	v_mfma_f32_16x16x32_bf16 v[100:103], v[208:211], v[168:171], v[100:103]
	v_mfma_f32_16x16x32_bf16 v[96:99], v[216:219], v[168:171], v[96:99]
	v_mfma_f32_16x16x32_bf16 v[84:87], v[208:211], v[176:179], v[84:87]
	v_mfma_f32_16x16x32_bf16 v[80:83], v[216:219], v[176:179], v[80:83]
	v_mfma_f32_16x16x32_bf16 v[68:71], v[208:211], v[200:203], v[68:71]
	v_mfma_f32_16x16x32_bf16 v[64:67], v[216:219], v[200:203], v[64:67]
	v_mfma_f32_16x16x32_bf16 v[116:119], v[212:215], v[164:167], v[116:119]
	v_mfma_f32_16x16x32_bf16 v[112:115], v[220:223], v[164:167], v[112:115]
	v_mfma_f32_16x16x32_bf16 v[100:103], v[212:215], v[172:175], v[100:103]
	v_mfma_f32_16x16x32_bf16 v[96:99], v[220:223], v[172:175], v[96:99]
	v_mfma_f32_16x16x32_bf16 v[84:87], v[212:215], v[196:199], v[84:87]
	v_mfma_f32_16x16x32_bf16 v[80:83], v[220:223], v[196:199], v[80:83]
	v_mfma_f32_16x16x32_bf16 v[68:71], v[212:215], v[204:207], v[68:71]
	v_mfma_f32_16x16x32_bf16 v[64:67], v[220:223], v[204:207], v[64:67]
	s_mov_b32 m0, s38
	s_add_u32 s100, s28, s0
	s_addc_u32 s101, s29, s1
	s_barrier
	ds_read_b128 v[158:161], v163 offset:16384
	ds_read_b128 v[164:167], v163 offset:17408
	ds_read_b128 v[168:171], v163 offset:18432
	ds_read_b128 v[172:175], v163 offset:19456
	ds_read_b128 v[176:179], v163 offset:20480
	ds_read_b128 v[196:199], v163 offset:21504
	ds_read_b128 v[200:203], v163 offset:22528
	ds_read_b128 v[204:207], v163 offset:23552
	global_load_lds_dwordx4 v128, s[28:29]
	s_mov_b32 m0, s39
	s_nop 0
	global_load_lds_dwordx4 v132, s[28:29]
	s_barrier
	s_waitcnt lgkmcnt(0)
	v_mfma_f32_16x16x32_bf16 v[60:63], v[140:143], v[158:161], v[60:63]
	v_mfma_f32_16x16x32_bf16 v[56:59], v[150:153], v[158:161], v[56:59]
	v_mfma_f32_16x16x32_bf16 v[44:47], v[140:143], v[168:171], v[44:47]
	v_mfma_f32_16x16x32_bf16 v[40:43], v[150:153], v[168:171], v[40:43]
	v_mfma_f32_16x16x32_bf16 v[28:31], v[140:143], v[176:179], v[28:31]
	v_mfma_f32_16x16x32_bf16 v[24:27], v[150:153], v[176:179], v[24:27]
	v_mfma_f32_16x16x32_bf16 v[12:15], v[140:143], v[200:203], v[12:15]
	v_mfma_f32_16x16x32_bf16 v[8:11], v[150:153], v[200:203], v[8:11]
	v_mfma_f32_16x16x32_bf16 v[60:63], v[146:149], v[164:167], v[60:63]
	v_mfma_f32_16x16x32_bf16 v[56:59], v[154:157], v[164:167], v[56:59]
	v_mfma_f32_16x16x32_bf16 v[44:47], v[146:149], v[172:175], v[44:47]
	v_mfma_f32_16x16x32_bf16 v[40:43], v[154:157], v[172:175], v[40:43]
	v_mfma_f32_16x16x32_bf16 v[28:31], v[146:149], v[196:199], v[28:31]
	v_mfma_f32_16x16x32_bf16 v[24:27], v[154:157], v[196:199], v[24:27]
	v_mfma_f32_16x16x32_bf16 v[12:15], v[146:149], v[204:207], v[12:15]
	v_mfma_f32_16x16x32_bf16 v[8:11], v[154:157], v[204:207], v[8:11]
	s_barrier
	s_add_u32 s18, s22, 0x18000
	s_addc_u32 s19, s23, 0
	s_add_i32 s55, s56, s35
	s_mov_b32 m0, s55
	s_nop 0
	global_load_lds_dwordx4 v130, s[18:19]
	s_add_i32 m0, s55, 0x2000
	s_nop 0
	global_load_lds_dwordx4 v134, s[18:19]
	s_waitcnt vmcnt(6)
	s_barrier
; #define PG8_STAGE(bufoff, gbase, voff) do { _Pragma("unroll") for (int _i = 0; _i < 2; ++_i) \
;     __builtin_amdgcn_global_load_lds((const unsigned*)((const char*)(gbase) + (voff)[_i]), (LAS unsigned*)(lds + (bufoff) + ldsw + _i * 8192), 16, 0, 0); } while (0)
; #define PG8_LDA(dst, b, h) do { _Pragma("unroll") for (int m = 0; m < 4; ++m) _Pragma("unroll") for (int k = 0; k < 2; ++k) dst[m][k] = *(const LAS bf16x8*)(lds + PG8_SA(b, h) + aoff + m * 2048 + k * 1024); } while (0)
; #define PG8_LDB(dst, b, h) do { _Pragma("unroll") for (int n = 0; n < 2; ++n) _Pragma("unroll") for (int k = 0; k < 2; ++k) dst[n][k] = *(const LAS bf16x8*)(lds + PG8_SB(b, h) + boff + n * 2048 + k * 1024); } while (0)
; #define PG8_MMA(ai, bj, At, Bt) do { __builtin_amdgcn_s_setprio(1); _Pragma("unroll") for (int m = 0; m < 4; ++m) _Pragma("unroll") for (int n = 0; n < 2; ++n) _Pragma("unroll") for (int k = 0; k < 2; ++k) \
;     acc[ai][bj][m][n] = __builtin_amdgcn_mfma_f32_16x16x32_bf16(Bt[n][k], At[m][k], acc[ai][bj][m][n], 0, 0, 0); __builtin_amdgcn_s_setprio(0); } while (0)
; #define PG8_WAIT_V(n) asm volatile("s_waitcnt vmcnt(" #n ")" ::: "memory")
; #define PG8_WAIT_L(n) asm volatile("s_waitcnt lgkmcnt(" #n ")" ::: "memory")
; #define PG8_BAR __builtin_amdgcn_s_barrier()
; #define PG8_SCHED __builtin_amdgcn_sched_barrier(0)
; template <class Epi, class Sched>
; DI void gemm_phase(LAS unsigned char* lds, const Gemm g, const Sched& S, const Epi& E) {
;     ...
;       PG8_WAIT_V(6); PG8_BAR; PG8_MMA(1, 1, At, B1); PG8_BAR;
;       PG8_LDB(B0, 1, 0); PG8_SCHED; PG8_LDA(At, 1, 0); PG8_STAGE(PG8_SA(0, 1), a2 + hstep, voffA);
;       PG8_WAIT_L(8); PG8_BAR; PG8_WAIT_L(0); PG8_MMA(0, 0, At, B0); PG8_BAR; PG8_SCHED;
;       PG8_LDB(B1, 1, 1); PG8_STAGE(PG8_SB(1, 0), b3, voffB);
;       PG8_BAR; PG8_WAIT_L(0); PG8_MMA(0, 1, At, B1); PG8_BAR;
;       PG8_LDA(At, 1, 1); PG8_STAGE(PG8_SA(1, 0), a3, voffA);
;       PG8_BAR; PG8_WAIT_L(0); PG8_MMA(1, 0, At, B0); PG8_BAR; PG8_SCHED;
	v_mfma_f32_16x16x32_bf16 v[52:55], v[208:211], v[158:161], v[52:55]
	v_mfma_f32_16x16x32_bf16 v[48:51], v[216:219], v[158:161], v[48:51]
	v_mfma_f32_16x16x32_bf16 v[36:39], v[208:211], v[168:171], v[36:39]
	v_mfma_f32_16x16x32_bf16 v[32:35], v[216:219], v[168:171], v[32:35]
	v_mfma_f32_16x16x32_bf16 v[20:23], v[208:211], v[176:179], v[20:23]
	v_mfma_f32_16x16x32_bf16 v[16:19], v[216:219], v[176:179], v[16:19]
	v_mfma_f32_16x16x32_bf16 v[4:7], v[208:211], v[200:203], v[4:7]
	v_mfma_f32_16x16x32_bf16 v[0:3], v[216:219], v[200:203], v[0:3]
	v_mfma_f32_16x16x32_bf16 v[52:55], v[212:215], v[164:167], v[52:55]
	v_mfma_f32_16x16x32_bf16 v[48:51], v[220:223], v[164:167], v[48:51]
	v_mfma_f32_16x16x32_bf16 v[36:39], v[212:215], v[172:175], v[36:39]
	v_mfma_f32_16x16x32_bf16 v[32:35], v[220:223], v[172:175], v[32:35]
	v_mfma_f32_16x16x32_bf16 v[20:23], v[212:215], v[196:199], v[20:23]
	v_mfma_f32_16x16x32_bf16 v[16:19], v[220:223], v[196:199], v[16:19]
	v_mfma_f32_16x16x32_bf16 v[4:7], v[212:215], v[204:207], v[4:7]
	v_mfma_f32_16x16x32_bf16 v[0:3], v[220:223], v[204:207], v[0:3]
	s_add_i32 s55, 0, 0x18000
	s_barrier
	ds_read_b128 v[140:143], v226
	ds_read_b128 v[146:149], v226 offset:1024
	ds_read_b128 v[150:153], v226 offset:2048
	ds_read_b128 v[154:157], v226 offset:3072
	s_add_u32 s18, s28, 0x18000
	s_addc_u32 s19, s29, 0
	s_mov_b32 m0, s40
	ds_read_b128 v[158:161], v163 offset:32768
	ds_read_b128 v[164:167], v163 offset:33792
	ds_read_b128 v[168:171], v163 offset:34816
	ds_read_b128 v[172:175], v163 offset:35840
	ds_read_b128 v[176:179], v163 offset:36864
	ds_read_b128 v[196:199], v163 offset:37888
	ds_read_b128 v[200:203], v163 offset:38912
	ds_read_b128 v[204:207], v163 offset:39936
	global_load_lds_dwordx4 v128, s[18:19]
	s_mov_b32 m0, s41
	s_nop 0
	global_load_lds_dwordx4 v132, s[18:19]
	s_waitcnt lgkmcnt(8)
	s_barrier
	s_waitcnt lgkmcnt(0)
	v_mfma_f32_16x16x32_bf16 v[124:127], v[140:143], v[158:161], v[124:127]
	v_mfma_f32_16x16x32_bf16 v[120:123], v[150:153], v[158:161], v[120:123]
	v_mfma_f32_16x16x32_bf16 v[108:111], v[140:143], v[168:171], v[108:111]
	v_mfma_f32_16x16x32_bf16 v[104:107], v[150:153], v[168:171], v[104:107]
	v_mfma_f32_16x16x32_bf16 v[92:95], v[140:143], v[176:179], v[92:95]
	v_mfma_f32_16x16x32_bf16 v[88:91], v[150:153], v[176:179], v[88:91]
	v_mfma_f32_16x16x32_bf16 v[76:79], v[140:143], v[200:203], v[76:79]
	v_mfma_f32_16x16x32_bf16 v[72:75], v[150:153], v[200:203], v[72:75]
	v_mfma_f32_16x16x32_bf16 v[124:127], v[146:149], v[164:167], v[124:127]
	v_mfma_f32_16x16x32_bf16 v[120:123], v[154:157], v[164:167], v[120:123]
	v_mfma_f32_16x16x32_bf16 v[108:111], v[146:149], v[172:175], v[108:111]
	v_mfma_f32_16x16x32_bf16 v[104:107], v[154:157], v[172:175], v[104:107]
	v_mfma_f32_16x16x32_bf16 v[92:95], v[146:149], v[196:199], v[92:95]
	v_mfma_f32_16x16x32_bf16 v[88:91], v[154:157], v[196:199], v[88:91]
	v_mfma_f32_16x16x32_bf16 v[76:79], v[146:149], v[204:207], v[76:79]
	v_mfma_f32_16x16x32_bf16 v[72:75], v[154:157], v[204:207], v[72:75]
	s_barrier
	s_add_i32 s28, 0, 0x1c000
	s_add_i32 s18, s55, s35
	s_mov_b32 m0, s18
	ds_read_b128 v[208:211], v227
	ds_read_b128 v[212:215], v227 offset:1024
	ds_read_b128 v[216:219], v227 offset:2048
	ds_read_b128 v[220:223], v227 offset:3072
	global_load_lds_dwordx4 v130, vcc
	s_add_i32 m0, s18, 0x2000
	s_nop 0
	global_load_lds_dwordx4 v134, vcc
	s_barrier
	s_waitcnt lgkmcnt(0)
	v_mfma_f32_16x16x32_bf16 v[116:119], v[208:211], v[158:161], v[116:119]
	v_mfma_f32_16x16x32_bf16 v[112:115], v[216:219], v[158:161], v[112:115]
	v_mfma_f32_16x16x32_bf16 v[100:103], v[208:211], v[168:171], v[100:103]
	v_mfma_f32_16x16x32_bf16 v[96:99], v[216:219], v[168:171], v[96:99]
	v_mfma_f32_16x16x32_bf16 v[84:87], v[208:211], v[176:179], v[84:87]
	v_mfma_f32_16x16x32_bf16 v[80:83], v[216:219], v[176:179], v[80:83]
	v_mfma_f32_16x16x32_bf16 v[68:71], v[208:211], v[200:203], v[68:71]
	v_mfma_f32_16x16x32_bf16 v[64:67], v[216:219], v[200:203], v[64:67]
	v_mfma_f32_16x16x32_bf16 v[116:119], v[212:215], v[164:167], v[116:119]
	v_mfma_f32_16x16x32_bf16 v[112:115], v[220:223], v[164:167], v[112:115]
	v_mfma_f32_16x16x32_bf16 v[100:103], v[212:215], v[172:175], v[100:103]
	v_mfma_f32_16x16x32_bf16 v[96:99], v[220:223], v[172:175], v[96:99]
	v_mfma_f32_16x16x32_bf16 v[84:87], v[212:215], v[196:199], v[84:87]
	v_mfma_f32_16x16x32_bf16 v[80:83], v[220:223], v[196:199], v[80:83]
	v_mfma_f32_16x16x32_bf16 v[68:71], v[212:215], v[204:207], v[68:71]
	v_mfma_f32_16x16x32_bf16 v[64:67], v[220:223], v[204:207], v[64:67]
	s_mov_b32 m0, s44
	s_barrier
	ds_read_b128 v[158:161], v163 offset:49152
	ds_read_b128 v[164:167], v163 offset:50176
	ds_read_b128 v[168:171], v163 offset:51200
	ds_read_b128 v[172:175], v163 offset:52224
	ds_read_b128 v[176:179], v163 offset:53248
	ds_read_b128 v[196:199], v163 offset:54272
	ds_read_b128 v[200:203], v163 offset:55296
	ds_read_b128 v[204:207], v163 offset:56320
	global_load_lds_dwordx4 v128, s[100:101]
	s_mov_b32 m0, s45
	s_nop 0
	global_load_lds_dwordx4 v132, s[100:101]
	s_barrier
	s_waitcnt lgkmcnt(0)
	v_mfma_f32_16x16x32_bf16 v[60:63], v[140:143], v[158:161], v[60:63]
	v_mfma_f32_16x16x32_bf16 v[56:59], v[150:153], v[158:161], v[56:59]
	v_mfma_f32_16x16x32_bf16 v[44:47], v[140:143], v[168:171], v[44:47]
	v_mfma_f32_16x16x32_bf16 v[40:43], v[150:153], v[168:171], v[40:43]
	v_mfma_f32_16x16x32_bf16 v[28:31], v[140:143], v[176:179], v[28:31]
	v_mfma_f32_16x16x32_bf16 v[24:27], v[150:153], v[176:179], v[24:27]
	v_mfma_f32_16x16x32_bf16 v[12:15], v[140:143], v[200:203], v[12:15]
	v_mfma_f32_16x16x32_bf16 v[8:11], v[150:153], v[200:203], v[8:11]
	v_mfma_f32_16x16x32_bf16 v[60:63], v[146:149], v[164:167], v[60:63]
	v_mfma_f32_16x16x32_bf16 v[56:59], v[154:157], v[164:167], v[56:59]
	v_mfma_f32_16x16x32_bf16 v[44:47], v[146:149], v[172:175], v[44:47]
	v_mfma_f32_16x16x32_bf16 v[40:43], v[154:157], v[172:175], v[40:43]
	v_mfma_f32_16x16x32_bf16 v[28:31], v[146:149], v[196:199], v[28:31]
	v_mfma_f32_16x16x32_bf16 v[24:27], v[154:157], v[196:199], v[24:27]
	v_mfma_f32_16x16x32_bf16 v[12:15], v[146:149], v[204:207], v[12:15]
	v_mfma_f32_16x16x32_bf16 v[8:11], v[154:157], v[204:207], v[8:11]
	s_barrier
; #define PG8_STAGE(bufoff, gbase, voff) do { _Pragma("unroll") for (int _i = 0; _i < 2; ++_i) \
;     __builtin_amdgcn_global_load_lds((const unsigned*)((const char*)(gbase) + (voff)[_i]), (LAS unsigned*)(lds + (bufoff) + ldsw + _i * 8192), 16, 0, 0); } while (0)
; #define PG8_LDA(dst, b, h) do { _Pragma("unroll") for (int m = 0; m < 4; ++m) _Pragma("unroll") for (int k = 0; k < 2; ++k) dst[m][k] = *(const LAS bf16x8*)(lds + PG8_SA(b, h) + aoff + m * 2048 + k * 1024); } while (0)
; #define PG8_LDB(dst, b, h) do { _Pragma("unroll") for (int n = 0; n < 2; ++n) _Pragma("unroll") for (int k = 0; k < 2; ++k) dst[n][k] = *(const LAS bf16x8*)(lds + PG8_SB(b, h) + boff + n * 2048 + k * 1024); } while (0)
; #define PG8_WAIT_V(n) asm volatile("s_waitcnt vmcnt(" #n ")" ::: "memory")
; #define PG8_WAIT_L(n) asm volatile("s_waitcnt lgkmcnt(" #n ")" ::: "memory")
; #define PG8_BAR __builtin_amdgcn_s_barrier()
; #define PG8_SCHED __builtin_amdgcn_sched_barrier(0)
; template <class Epi, class Sched>
; DI void gemm_phase(LAS unsigned char* lds, const Gemm g, const Sched& S, const Epi& E) {
;     ...
;       PG8_WAIT_V(6); PG8_BAR; PG8_MMA(1, 1, At, B1); PG8_BAR;
;       PG8_LDB(B0, 1, 0); PG8_SCHED; PG8_LDA(At, 1, 0); PG8_STAGE(PG8_SA(0, 1), a2 + hstep, voffA);
;       PG8_WAIT_L(8); PG8_BAR; PG8_WAIT_L(0); PG8_MMA(0, 0, At, B0); PG8_BAR; PG8_SCHED;
;       PG8_LDB(B1, 1, 1); PG8_STAGE(PG8_SB(1, 0), b3, voffB);
;       PG8_BAR; PG8_WAIT_L(0); PG8_MMA(0, 1, At, B1); PG8_BAR;
;       PG8_LDA(At, 1, 1); PG8_STAGE(PG8_SA(1, 0), a3, voffA);
;       PG8_BAR; PG8_WAIT_L(0); PG8_MMA(1, 0, At, B0); PG8_BAR; PG8_SCHED;
;       PG8_STAGE(PG8_SB(1, 1), b3 + hstep, voffB);
;       PG8_WAIT_V(6); PG8_BAR; PG8_MMA(1, 1, At, B1); PG8_BAR;
;   DI void operator()(const f32x4 (&acc)[2][2][4][2], const pg8::Unit& u, int wr, int wc, int fr_, int fq_) const {
;     ...
;             } else if (EPI == EPI_UQ) {
;               if (n == 0) {
;                 const float sc = rinv * (0.10206207261596575f * LOG2E);
;                 const int gb = u.pn * 256 + bj * 128 + wc * 32;
;                 const int hd = gb / 96; const int within = gb - hd * 96;
;                 f32x4 a0 = v, a1 = acc[ai][bj][m][1];
;                 if (within == 64) rope_perm(a0, a1, fq, t_ & 63, tcos, tsin, token & (S_ - 1));
;                 st_bf8((u16*)(big + E_QMLA) + (size_t)token * 768 + gb + 8 * fq, a0, a1, sc);
;               }
	s_add_u32 s18, s22, 0x18080
	s_addc_u32 s19, s23, 0
	s_add_i32 s22, s28, s35
	s_mov_b32 m0, s22
	s_nop 0
	global_load_lds_dwordx4 v130, s[18:19]
	s_add_i32 m0, s22, 0x2000
	s_nop 0
	global_load_lds_dwordx4 v134, s[18:19]
	s_waitcnt vmcnt(6)
	s_barrier
	v_mfma_f32_16x16x32_bf16 v[52:55], v[208:211], v[158:161], v[52:55]
	v_mfma_f32_16x16x32_bf16 v[48:51], v[216:219], v[158:161], v[48:51]
	v_mfma_f32_16x16x32_bf16 v[36:39], v[208:211], v[168:171], v[36:39]
	v_mfma_f32_16x16x32_bf16 v[32:35], v[216:219], v[168:171], v[32:35]
	v_mfma_f32_16x16x32_bf16 v[20:23], v[208:211], v[176:179], v[20:23]
	v_mfma_f32_16x16x32_bf16 v[16:19], v[216:219], v[176:179], v[16:19]
	v_mfma_f32_16x16x32_bf16 v[4:7], v[208:211], v[200:203], v[4:7]
	v_mfma_f32_16x16x32_bf16 v[0:3], v[216:219], v[200:203], v[0:3]
	v_mfma_f32_16x16x32_bf16 v[52:55], v[212:215], v[164:167], v[52:55]
	v_mfma_f32_16x16x32_bf16 v[48:51], v[220:223], v[164:167], v[48:51]
	v_mfma_f32_16x16x32_bf16 v[36:39], v[212:215], v[172:175], v[36:39]
	v_mfma_f32_16x16x32_bf16 v[32:35], v[220:223], v[172:175], v[32:35]
	v_mfma_f32_16x16x32_bf16 v[20:23], v[212:215], v[196:199], v[20:23]
	v_mfma_f32_16x16x32_bf16 v[16:19], v[220:223], v[196:199], v[16:19]
	v_mfma_f32_16x16x32_bf16 v[4:7], v[212:215], v[204:207], v[4:7]
	v_mfma_f32_16x16x32_bf16 v[0:3], v[220:223], v[204:207], v[0:3]
	s_add_i32 s54, s54, 2
	s_add_u32 s52, s52, 0x100
	s_addc_u32 s53, s53, 0
	s_cmp_gt_u32 s54, 3
	s_mov_b64 s[18:19], s[20:21]
	s_barrier
	s_cbranch_scc0 .LBB0_1202
	v_mov_b32_e32 v140, v182
	s_lshl_b32 s19, s51, 10
	s_lshl_b32 s18, s49, 8
	s_or_b32 s18, s18, s43
	v_and_or_b32 v167, v140, 15, s42
	v_lshlrev_b32_e32 v141, 2, v140
	s_movk_i32 s20, 0x80
	s_add_i32 s19, s19, 0
	v_bitop3_b32 v164, v141, s20, v190 bitop3:0x6c
	v_lshl_add_u32 v141, v167, 2, s19
	s_mul_hi_i32 s19, s18, 0x2aaaaaab
	v_add_u32_e32 v166, 0x20000, v141
	s_lshr_b32 s20, s19, 31
	s_lshr_b32 s19, s19, 4
	s_lshl_b32 s50, s50, 8
	ds_read_b32 v144, v166
	s_add_i32 s19, s19, s20
	v_add_u32_e32 v165, s50, v167
	s_mulk_i32 s19, 0x60
	v_bfe_u32 v168, v140, 4, 2
	v_lshrrev_b32_e32 v140, 1, v140
	v_lshlrev_b32_e32 v141, 4, v165
	s_sub_i32 s19, s18, s19
	v_and_b32_e32 v140, 8, v140
	v_and_b32_e32 v141, 0xfcf0, v141
	s_cmp_eq_u32 s19, 64
	v_cmp_lt_u32_e64 s[78:79], 1, v168
	s_cselect_b64 s[20:21], -1, 0
	s_cmp_lg_u32 s19, 64
	v_lshlrev_b32_e32 v142, 2, v141
	v_lshlrev_b32_e32 v140, 2, v140
	s_cbranch_scc1 .LBB0_1209
	v_mov_b32_e32 v143, v145
	v_lshl_add_u64 v[146:147], s[12:13], 0, v[142:143]
	v_mov_b32_e32 v141, v145
	v_lshl_add_u64 v[152:153], s[14:15], 0, v[142:143]
	v_lshl_add_u64 v[146:147], v[146:147], 0, v[140:141]
	v_lshl_add_u64 v[152:153], v[152:153], 0, v[140:141]
	global_load_dwordx4 v[148:151], v[146:147], off
	global_load_dwordx4 v[154:157], v[152:153], off
	global_load_dwordx4 v[170:173], v[152:153], off offset:16
	global_load_dwordx4 v[174:177], v[146:147], off offset:16
	global_load_dwordx4 v[212:215], v[146:147], off offset:1024
	global_load_dwordx4 v[216:219], v[152:153], off offset:1024
	global_load_dwordx4 v[220:223], v[152:153], off offset:1040
	global_load_dwordx4 v[224:227], v[146:147], off offset:1040
	ds_bpermute_b32 v152, v164, v124
	ds_bpermute_b32 v160, v164, v120
	ds_bpermute_b32 v153, v164, v125
	ds_bpermute_b32 v161, v164, v121
	ds_bpermute_b32 v158, v164, v126
	ds_bpermute_b32 v178, v164, v122
	ds_bpermute_b32 v159, v164, v127
	ds_bpermute_b32 v179, v164, v123
	s_waitcnt vmcnt(4) lgkmcnt(0)
	v_pk_mul_f32 v[154:155], v[154:155], v[152:153]
	v_pk_mul_f32 v[146:147], v[126:127], v[150:151]
	v_pk_mul_f32 v[150:151], v[124:125], v[148:149]
	v_pk_mul_f32 v[158:159], v[156:157], v[158:159]
	v_pk_mul_f32 v[148:149], v[170:171], v[160:161]
	v_pk_mul_f32 v[152:153], v[172:173], v[178:179]
	v_pk_mul_f32 v[156:157], v[122:123], v[176:177]
	v_pk_mul_f32 v[160:161], v[120:121], v[174:175]
	s_and_saveexec_b64 s[22:23], s[78:79]
	s_xor_b64 s[22:23], exec, s[22:23]
	v_pk_add_f32 v[126:127], v[146:147], v[158:159]
	v_pk_add_f32 v[124:125], v[150:151], v[154:155]
	v_pk_add_f32 v[122:123], v[156:157], v[152:153]
	v_pk_add_f32 v[120:121], v[160:161], v[148:149]
	s_andn2_saveexec_b64 s[22:23], s[22:23]
	v_sub_f32_e32 v127, v147, v159
	v_sub_f32_e32 v126, v146, v158
	v_sub_f32_e32 v125, v151, v155
	v_sub_f32_e32 v124, v150, v154
	v_sub_f32_e32 v123, v157, v153
	v_sub_f32_e32 v122, v156, v152
	v_sub_f32_e32 v121, v161, v149
	v_sub_f32_e32 v120, v160, v148
	s_or_b64 exec, exec, s[22:23]
; DI void rope_perm(f32x4& a0, f32x4& a1, int fq, int lane, const float* tcos, const float* tsin, int pos) {
;   f32x4 p0, p1;
; #pragma unroll
;   for (int e = 0; e < 4; ++e) { p0[e] = shx(a0[e], 32, lane); p1[e] = shx(a1[e], 32, lane); }
;   const int jb = 8 * (fq & 1);
;   const f32x4 c0 = *(const f32x4*)(tcos + pos * 16 + jb), c1 = *(const f32x4*)(tcos + pos * 16 + jb + 4);
;   const f32x4 s0 = *(const f32x4*)(tsin + pos * 16 + jb), s1 = *(const f32x4*)(tsin + pos * 16 + jb + 4);
;   if (fq < 2) { a0 = a0 * c0 - p0 * s0; a1 = a1 * c1 - p1 * s1; }
;   else        { a0 = a0 * c0 + p0 * s0; a1 = a1 * c1 + p1 * s1; }
; }
;   DI void operator()(const f32x4 (&acc)[2][2][4][2], const pg8::Unit& u, int wr, int wc, int fr_, int fq_) const {
;     ...
;             } else if (EPI == EPI_UQ) {
;               if (n == 0) {
;                 const float sc = rinv * (0.10206207261596575f * LOG2E);
;                 const int gb = u.pn * 256 + bj * 128 + wc * 32;
;                 const int hd = gb / 96; const int within = gb - hd * 96;
;                 f32x4 a0 = v, a1 = acc[ai][bj][m][1];
;                 if (within == 64) rope_perm(a0, a1, fq, t_ & 63, tcos, tsin, token & (S_ - 1));
;                 st_bf8((u16*)(big + E_QMLA) + (size_t)token * 768 + gb + 8 * fq, a0, a1, sc);
;               }
.LBB0_1209:
	v_mov_b64_e32 v[148:149], s[16:17]
	s_movk_i32 s22, 0x600
	v_mad_i64_i32 v[148:149], s[22:23], v165, s22, v[148:149]
	s_or_b32 s22, s18, 0x80
	s_mul_hi_i32 s23, s22, 0x2aaaaaab
	s_lshr_b32 s28, s23, 31
	s_lshr_b32 s23, s23, 4
	s_add_i32 s23, s23, s28
	s_waitcnt lgkmcnt(0)
	v_mul_f32_e32 v146, 0x3e16c740, v144
	s_mulk_i32 s23, 0x60
	s_ashr_i32 s19, s18, 31
	v_pk_mul_f32 v[124:125], v[146:147], v[124:125] op_sel_hi:[0,1]
	v_pk_mul_f32 v[126:127], v[146:147], v[126:127] op_sel_hi:[0,1]
	v_pk_mul_f32 v[120:121], v[146:147], v[120:121] op_sel_hi:[0,1]
	s_sub_i32 s28, s22, s23
	v_lshl_add_u64 v[148:149], s[18:19], 1, v[148:149]
	v_lshlrev_b32_e32 v144, 4, v168
	v_cvt_pk_bf16_f32 v124, v124, v125
	v_cvt_pk_bf16_f32 v125, v126, v127
	v_cvt_pk_bf16_f32 v126, v120, v121
	v_pk_mul_f32 v[120:121], v[146:147], v[122:123] op_sel_hi:[0,1]
	s_cmp_eq_u32 s28, 64
	v_lshl_add_u64 v[148:149], v[148:149], 0, v[144:145]
	v_cvt_pk_bf16_f32 v127, v120, v121
	s_cselect_b64 s[22:23], -1, 0
	s_cmp_lg_u32 s28, 64
	global_store_dwordx4 v[148:149], v[124:127], off
	s_cbranch_scc1 .LBB0_1215
	v_mov_b32_e32 v143, v145
	v_lshl_add_u64 v[120:121], s[12:13], 0, v[142:143]
	v_mov_b32_e32 v141, v145
	v_lshl_add_u64 v[126:127], s[14:15], 0, v[142:143]
	v_lshl_add_u64 v[120:121], v[120:121], 0, v[140:141]
	v_lshl_add_u64 v[126:127], v[126:127], 0, v[140:141]
	global_load_dwordx4 v[122:125], v[120:121], off
	global_load_dwordx4 v[150:153], v[126:127], off
	global_load_dwordx4 v[154:157], v[126:127], off offset:16
	global_load_dwordx4 v[158:161], v[120:121], off offset:16
	global_load_dwordx4 v[212:215], v[120:121], off offset:1024
	global_load_dwordx4 v[216:219], v[126:127], off offset:1024
	global_load_dwordx4 v[220:223], v[126:127], off offset:1040
	global_load_dwordx4 v[224:227], v[120:121], off offset:1040
	ds_bpermute_b32 v126, v164, v116
	ds_bpermute_b32 v170, v164, v112
	ds_bpermute_b32 v127, v164, v117
	ds_bpermute_b32 v171, v164, v113
	ds_bpermute_b32 v172, v164, v118
	ds_bpermute_b32 v174, v164, v114
	ds_bpermute_b32 v173, v164, v119
	ds_bpermute_b32 v175, v164, v115
	s_waitcnt vmcnt(4) lgkmcnt(0)
	v_pk_mul_f32 v[142:143], v[150:151], v[126:127]
	v_pk_mul_f32 v[120:121], v[118:119], v[124:125]
	v_pk_mul_f32 v[124:125], v[116:117], v[122:123]
	v_pk_mul_f32 v[152:153], v[152:153], v[172:173]
	v_pk_mul_f32 v[122:123], v[154:155], v[170:171]
	v_pk_mul_f32 v[126:127], v[156:157], v[174:175]
	v_pk_mul_f32 v[150:151], v[114:115], v[160:161]
	v_pk_mul_f32 v[154:155], v[112:113], v[158:159]
	s_and_saveexec_b64 s[28:29], s[78:79]
	s_xor_b64 s[28:29], exec, s[28:29]
	v_pk_add_f32 v[118:119], v[120:121], v[152:153]
	v_pk_add_f32 v[116:117], v[124:125], v[142:143]
	v_pk_add_f32 v[114:115], v[150:151], v[126:127]
	v_pk_add_f32 v[112:113], v[154:155], v[122:123]
	s_andn2_saveexec_b64 s[28:29], s[28:29]
	v_sub_f32_e32 v119, v121, v153
	v_sub_f32_e32 v118, v120, v152
	v_sub_f32_e32 v117, v125, v143
	v_sub_f32_e32 v116, v124, v142
	v_sub_f32_e32 v115, v151, v127
	v_sub_f32_e32 v114, v150, v126
	v_sub_f32_e32 v113, v155, v123
	v_sub_f32_e32 v112, v154, v122
	s_or_b64 exec, exec, s[28:29]
.LBB0_1215:
	v_mov_b32_e32 v147, v146
	v_pk_mul_f32 v[116:117], v[146:147], v[116:117]
	v_pk_mul_f32 v[118:119], v[146:147], v[118:119]
	v_pk_mul_f32 v[112:113], v[146:147], v[112:113]
	v_cvt_pk_bf16_f32 v116, v116, v117
	v_cvt_pk_bf16_f32 v117, v118, v119
	v_cvt_pk_bf16_f32 v118, v112, v113
	v_pk_mul_f32 v[112:113], v[146:147], v[114:115]
	ds_read_b32 v146, v166 offset:64
	v_add3_u32 v144, s50, v167, 16
	v_cvt_pk_bf16_f32 v119, v112, v113
	v_lshlrev_b32_e32 v112, 4, v144
	v_and_b32_e32 v112, 0xfdf0, v112
	v_cndmask_b32_e64 v113, 0, 1, s[20:21]
	v_cmp_ne_u32_e64 s[70:71], 1, v113
	s_andn2_b64 vcc, exec, s[20:21]
	v_lshlrev_b32_e32 v112, 2, v112
	global_store_dwordx4 v[148:149], v[116:119], off offset:256
	s_cbranch_vccnz .LBB0_1221
	v_mov_b32_e32 v113, v145
	v_lshl_add_u64 v[114:115], s[12:13], 0, v[112:113]
	v_mov_b32_e32 v141, v145
	v_lshl_add_u64 v[120:121], s[14:15], 0, v[112:113]
	v_lshl_add_u64 v[114:115], v[114:115], 0, v[140:141]
	v_lshl_add_u64 v[120:121], v[120:121], 0, v[140:141]
	global_load_dwordx4 v[196:199], v[114:115], off offset:1024
	global_load_dwordx4 v[200:203], v[120:121], off offset:1024
	global_load_dwordx4 v[204:207], v[120:121], off offset:1040
	global_load_dwordx4 v[208:211], v[114:115], off offset:1040
	ds_bpermute_b32 v120, v164, v108
	ds_bpermute_b32 v142, v164, v104
	ds_bpermute_b32 v121, v164, v109
	ds_bpermute_b32 v143, v164, v105
	ds_bpermute_b32 v126, v164, v110
	ds_bpermute_b32 v156, v164, v106
	ds_bpermute_b32 v127, v164, v111
	ds_bpermute_b32 v157, v164, v107
	s_waitcnt vmcnt(4) lgkmcnt(0)
	v_mov_b64_e32 v[116:117], v[212:213]
	v_mov_b64_e32 v[118:119], v[214:215]
	v_mov_b64_e32 v[122:123], v[216:217]
	v_mov_b64_e32 v[124:125], v[218:219]
	v_mov_b64_e32 v[148:149], v[220:221]
	v_mov_b64_e32 v[150:151], v[222:223]
	v_mov_b64_e32 v[152:153], v[224:225]
	v_mov_b64_e32 v[154:155], v[226:227]
	v_pk_mul_f32 v[122:123], v[122:123], v[120:121]
	v_pk_mul_f32 v[114:115], v[110:111], v[118:119]
	v_pk_mul_f32 v[118:119], v[108:109], v[116:117]
	v_pk_mul_f32 v[126:127], v[124:125], v[126:127]
	v_pk_mul_f32 v[116:117], v[148:149], v[142:143]
	v_pk_mul_f32 v[120:121], v[150:151], v[156:157]
	v_pk_mul_f32 v[124:125], v[106:107], v[154:155]
	v_pk_mul_f32 v[142:143], v[104:105], v[152:153]
	s_and_saveexec_b64 s[20:21], s[78:79]
	s_xor_b64 s[20:21], exec, s[20:21]
	v_pk_add_f32 v[110:111], v[114:115], v[126:127]
	v_pk_add_f32 v[108:109], v[118:119], v[122:123]
	v_pk_add_f32 v[106:107], v[124:125], v[120:121]
	v_pk_add_f32 v[104:105], v[142:143], v[116:117]
	s_andn2_saveexec_b64 s[20:21], s[20:21]
	v_sub_f32_e32 v111, v115, v127
	v_sub_f32_e32 v110, v114, v126
	v_sub_f32_e32 v109, v119, v123
	v_sub_f32_e32 v108, v118, v122
	v_sub_f32_e32 v107, v125, v121
	v_sub_f32_e32 v106, v124, v120
	v_sub_f32_e32 v105, v143, v117
	v_sub_f32_e32 v104, v142, v116
	s_or_b64 exec, exec, s[20:21]
; DI void rope_perm(f32x4& a0, f32x4& a1, int fq, int lane, const float* tcos, const float* tsin, int pos) {
;   f32x4 p0, p1;
; #pragma unroll
;   for (int e = 0; e < 4; ++e) { p0[e] = shx(a0[e], 32, lane); p1[e] = shx(a1[e], 32, lane); }
;   const int jb = 8 * (fq & 1);
;   const f32x4 c0 = *(const f32x4*)(tcos + pos * 16 + jb), c1 = *(const f32x4*)(tcos + pos * 16 + jb + 4);
;   const f32x4 s0 = *(const f32x4*)(tsin + pos * 16 + jb), s1 = *(const f32x4*)(tsin + pos * 16 + jb + 4);
;   if (fq < 2) { a0 = a0 * c0 - p0 * s0; a1 = a1 * c1 - p1 * s1; }
;   else        { a0 = a0 * c0 + p0 * s0; a1 = a1 * c1 + p1 * s1; }
; }
;   DI void operator()(const f32x4 (&acc)[2][2][4][2], const pg8::Unit& u, int wr, int wc, int fr_, int fq_) const {
;     ...
;             } else if (EPI == EPI_UQ) {
;               if (n == 0) {
;                 const float sc = rinv * (0.10206207261596575f * LOG2E);
;                 const int gb = u.pn * 256 + bj * 128 + wc * 32;
;                 const int hd = gb / 96; const int within = gb - hd * 96;
;                 f32x4 a0 = v, a1 = acc[ai][bj][m][1];
;                 if (within == 64) rope_perm(a0, a1, fq, t_ & 63, tcos, tsin, token & (S_ - 1));
;                 st_bf8((u16*)(big + E_QMLA) + (size_t)token * 768 + gb + 8 * fq, a0, a1, sc);
;               }
.LBB0_1221:
	s_waitcnt lgkmcnt(0)
	v_mul_f32_e32 v114, 0x3e16c740, v146
	v_mov_b64_e32 v[116:117], s[16:17]
	s_movk_i32 s20, 0x600
	v_pk_mul_f32 v[108:109], v[114:115], v[108:109] op_sel_hi:[0,1]
	v_pk_mul_f32 v[110:111], v[114:115], v[110:111] op_sel_hi:[0,1]
	v_pk_mul_f32 v[104:105], v[114:115], v[104:105] op_sel_hi:[0,1]
	v_lshlrev_b32_e32 v113, 3, v168
	v_mad_i64_i32 v[116:117], s[20:21], v144, s20, v[116:117]
	v_cvt_pk_bf16_f32 v108, v108, v109
	v_cvt_pk_bf16_f32 v109, v110, v111
	v_cvt_pk_bf16_f32 v110, v104, v105
	v_pk_mul_f32 v[104:105], v[114:115], v[106:107] op_sel_hi:[0,1]
	v_lshl_add_u64 v[116:117], s[18:19], 1, v[116:117]
	v_lshlrev_b32_e32 v144, 1, v113
	v_cvt_pk_bf16_f32 v111, v104, v105
	v_cndmask_b32_e64 v104, 0, 1, s[22:23]
	v_lshl_add_u64 v[116:117], v[116:117], 0, v[144:145]
	v_cmp_ne_u32_e64 s[72:73], 1, v104
	s_andn2_b64 vcc, exec, s[22:23]
	global_store_dwordx4 v[116:117], v[108:111], off
	s_cbranch_vccnz .LBB0_1227
	v_mov_b32_e32 v113, v145
	v_lshl_add_u64 v[104:105], s[12:13], 0, v[112:113]
	v_mov_b32_e32 v141, v145
	v_lshl_add_u64 v[110:111], s[14:15], 0, v[112:113]
	v_lshl_add_u64 v[104:105], v[104:105], 0, v[140:141]
	v_lshl_add_u64 v[110:111], v[110:111], 0, v[140:141]
	global_load_dwordx4 v[196:199], v[104:105], off offset:1024
	global_load_dwordx4 v[200:203], v[110:111], off offset:1024
	global_load_dwordx4 v[204:207], v[110:111], off offset:1040
	global_load_dwordx4 v[208:211], v[104:105], off offset:1040
	ds_bpermute_b32 v110, v164, v100
	ds_bpermute_b32 v126, v164, v96
	ds_bpermute_b32 v111, v164, v101
	ds_bpermute_b32 v127, v164, v97
	ds_bpermute_b32 v142, v164, v102
	ds_bpermute_b32 v150, v164, v98
	ds_bpermute_b32 v143, v164, v103
	ds_bpermute_b32 v151, v164, v99
	s_waitcnt vmcnt(4) lgkmcnt(0)
	v_mov_b64_e32 v[106:107], v[212:213]
	v_mov_b64_e32 v[108:109], v[214:215]
	v_mov_b64_e32 v[118:119], v[216:217]
	v_mov_b64_e32 v[120:121], v[218:219]
	v_mov_b64_e32 v[122:123], v[220:221]
	v_mov_b64_e32 v[124:125], v[222:223]
	v_mov_b64_e32 v[146:147], v[224:225]
	v_mov_b64_e32 v[148:149], v[226:227]
	v_pk_mul_f32 v[112:113], v[118:119], v[110:111]
	v_pk_mul_f32 v[104:105], v[102:103], v[108:109]
	v_pk_mul_f32 v[108:109], v[100:101], v[106:107]
	v_pk_mul_f32 v[120:121], v[120:121], v[142:143]
	v_pk_mul_f32 v[106:107], v[122:123], v[126:127]
	v_pk_mul_f32 v[110:111], v[124:125], v[150:151]
	v_pk_mul_f32 v[118:119], v[98:99], v[148:149]
	v_pk_mul_f32 v[122:123], v[96:97], v[146:147]
	s_and_saveexec_b64 s[20:21], s[78:79]
	s_xor_b64 s[20:21], exec, s[20:21]
	v_pk_add_f32 v[102:103], v[104:105], v[120:121]
	v_pk_add_f32 v[100:101], v[108:109], v[112:113]
	v_pk_add_f32 v[98:99], v[118:119], v[110:111]
	v_pk_add_f32 v[96:97], v[122:123], v[106:107]
	s_andn2_saveexec_b64 s[20:21], s[20:21]
	v_sub_f32_e32 v103, v105, v121
	v_sub_f32_e32 v102, v104, v120
	v_sub_f32_e32 v101, v109, v113
	v_sub_f32_e32 v100, v108, v112
	v_sub_f32_e32 v99, v119, v111
	v_sub_f32_e32 v98, v118, v110
	v_sub_f32_e32 v97, v123, v107
	v_sub_f32_e32 v96, v122, v106
	s_or_b64 exec, exec, s[20:21]
.LBB0_1227:
	v_mov_b32_e32 v115, v114
	v_pk_mul_f32 v[100:101], v[114:115], v[100:101]
	v_pk_mul_f32 v[102:103], v[114:115], v[102:103]
	v_pk_mul_f32 v[96:97], v[114:115], v[96:97]
	v_cvt_pk_bf16_f32 v100, v100, v101
	v_cvt_pk_bf16_f32 v101, v102, v103
	v_cvt_pk_bf16_f32 v102, v96, v97
	v_pk_mul_f32 v[96:97], v[114:115], v[98:99]
	ds_read_b32 v115, v166 offset:128
	v_add3_u32 v114, s50, v167, 32
	v_cvt_pk_bf16_f32 v103, v96, v97
	v_lshlrev_b32_e32 v96, 4, v114
	v_and_b32_e32 v96, 0xfef0, v96
	s_and_b64 vcc, exec, s[70:71]
	v_lshlrev_b32_e32 v96, 2, v96
	global_store_dwordx4 v[116:117], v[100:103], off offset:256
	s_cbranch_vccnz .LBB0_1233
	v_mov_b32_e32 v97, v145
	v_lshl_add_u64 v[98:99], s[12:13], 0, v[96:97]
	v_mov_b32_e32 v141, v145
	v_lshl_add_u64 v[104:105], s[14:15], 0, v[96:97]
	v_lshl_add_u64 v[98:99], v[98:99], 0, v[140:141]
	v_lshl_add_u64 v[104:105], v[104:105], 0, v[140:141]
	global_load_dwordx4 v[212:215], v[98:99], off offset:1024
	global_load_dwordx4 v[216:219], v[104:105], off offset:1024
	global_load_dwordx4 v[220:223], v[104:105], off offset:1040
	global_load_dwordx4 v[224:227], v[98:99], off offset:1040
	ds_bpermute_b32 v104, v164, v92
	ds_bpermute_b32 v112, v164, v88
	ds_bpermute_b32 v105, v164, v93
	ds_bpermute_b32 v113, v164, v89
	ds_bpermute_b32 v110, v164, v94
	ds_bpermute_b32 v124, v164, v90
	ds_bpermute_b32 v111, v164, v95
	ds_bpermute_b32 v125, v164, v91
	s_waitcnt vmcnt(4) lgkmcnt(0)
	v_mov_b64_e32 v[100:101], v[196:197]
	v_mov_b64_e32 v[102:103], v[198:199]
	v_mov_b64_e32 v[106:107], v[200:201]
	v_mov_b64_e32 v[108:109], v[202:203]
	v_mov_b64_e32 v[116:117], v[204:205]
	v_mov_b64_e32 v[118:119], v[206:207]
	v_mov_b64_e32 v[120:121], v[208:209]
	v_mov_b64_e32 v[122:123], v[210:211]
	v_pk_mul_f32 v[106:107], v[106:107], v[104:105]
	v_pk_mul_f32 v[98:99], v[94:95], v[102:103]
	v_pk_mul_f32 v[102:103], v[92:93], v[100:101]
	v_pk_mul_f32 v[110:111], v[108:109], v[110:111]
	v_pk_mul_f32 v[100:101], v[116:117], v[112:113]
	v_pk_mul_f32 v[104:105], v[118:119], v[124:125]
	v_pk_mul_f32 v[108:109], v[90:91], v[122:123]
	v_pk_mul_f32 v[112:113], v[88:89], v[120:121]
	s_and_saveexec_b64 s[20:21], s[78:79]
	s_xor_b64 s[20:21], exec, s[20:21]
	v_pk_add_f32 v[94:95], v[98:99], v[110:111]
	v_pk_add_f32 v[92:93], v[102:103], v[106:107]
	v_pk_add_f32 v[90:91], v[108:109], v[104:105]
	v_pk_add_f32 v[88:89], v[112:113], v[100:101]
	s_andn2_saveexec_b64 s[20:21], s[20:21]
	v_sub_f32_e32 v95, v99, v111
	v_sub_f32_e32 v94, v98, v110
	v_sub_f32_e32 v93, v103, v107
	v_sub_f32_e32 v92, v102, v106
	v_sub_f32_e32 v91, v109, v105
	v_sub_f32_e32 v90, v108, v104
	v_sub_f32_e32 v89, v113, v101
	v_sub_f32_e32 v88, v112, v100
	s_or_b64 exec, exec, s[20:21]
; DI void rope_perm(f32x4& a0, f32x4& a1, int fq, int lane, const float* tcos, const float* tsin, int pos) {
;   f32x4 p0, p1;
; #pragma unroll
;   for (int e = 0; e < 4; ++e) { p0[e] = shx(a0[e], 32, lane); p1[e] = shx(a1[e], 32, lane); }
;   const int jb = 8 * (fq & 1);
;   const f32x4 c0 = *(const f32x4*)(tcos + pos * 16 + jb), c1 = *(const f32x4*)(tcos + pos * 16 + jb + 4);
;   const f32x4 s0 = *(const f32x4*)(tsin + pos * 16 + jb), s1 = *(const f32x4*)(tsin + pos * 16 + jb + 4);
;   if (fq < 2) { a0 = a0 * c0 - p0 * s0; a1 = a1 * c1 - p1 * s1; }
;   else        { a0 = a0 * c0 + p0 * s0; a1 = a1 * c1 + p1 * s1; }
; }
;   DI void operator()(const f32x4 (&acc)[2][2][4][2], const pg8::Unit& u, int wr, int wc, int fr_, int fq_) const {
;     ...
;             } else if (EPI == EPI_UQ) {
;               if (n == 0) {
;                 const float sc = rinv * (0.10206207261596575f * LOG2E);
;                 const int gb = u.pn * 256 + bj * 128 + wc * 32;
;                 const int hd = gb / 96; const int within = gb - hd * 96;
;                 f32x4 a0 = v, a1 = acc[ai][bj][m][1];
;                 if (within == 64) rope_perm(a0, a1, fq, t_ & 63, tcos, tsin, token & (S_ - 1));
;                 st_bf8((u16*)(big + E_QMLA) + (size_t)token * 768 + gb + 8 * fq, a0, a1, sc);
;               }
.LBB0_1233:
	s_waitcnt lgkmcnt(0)
	v_mul_f32_e32 v98, 0x3e16c740, v115
	v_mov_b64_e32 v[100:101], s[16:17]
	s_movk_i32 s20, 0x600
	v_mad_i64_i32 v[100:101], s[20:21], v114, s20, v[100:101]
	v_pk_mul_f32 v[92:93], v[98:99], v[92:93] op_sel_hi:[0,1]
	v_pk_mul_f32 v[94:95], v[98:99], v[94:95] op_sel_hi:[0,1]
	v_pk_mul_f32 v[88:89], v[98:99], v[88:89] op_sel_hi:[0,1]
	v_lshl_add_u64 v[100:101], s[18:19], 1, v[100:101]
	v_cvt_pk_bf16_f32 v92, v92, v93
	v_cvt_pk_bf16_f32 v93, v94, v95
	v_cvt_pk_bf16_f32 v94, v88, v89
	v_pk_mul_f32 v[88:89], v[98:99], v[90:91] op_sel_hi:[0,1]
	v_lshl_add_u64 v[100:101], v[100:101], 0, v[144:145]
	v_cvt_pk_bf16_f32 v95, v88, v89
	s_and_b64 vcc, exec, s[72:73]
	global_store_dwordx4 v[100:101], v[92:95], off
	s_cbranch_vccnz .LBB0_1239
	v_mov_b32_e32 v97, v145
	v_lshl_add_u64 v[88:89], s[12:13], 0, v[96:97]
	v_mov_b32_e32 v141, v145
	v_lshl_add_u64 v[94:95], s[14:15], 0, v[96:97]
	v_lshl_add_u64 v[88:89], v[88:89], 0, v[140:141]
	v_lshl_add_u64 v[94:95], v[94:95], 0, v[140:141]
	global_load_dwordx4 v[212:215], v[88:89], off offset:1024
	global_load_dwordx4 v[216:219], v[94:95], off offset:1024
	global_load_dwordx4 v[220:223], v[94:95], off offset:1040
	global_load_dwordx4 v[224:227], v[88:89], off offset:1040
	ds_bpermute_b32 v94, v164, v84
	ds_bpermute_b32 v114, v164, v80
	ds_bpermute_b32 v95, v164, v85
	ds_bpermute_b32 v115, v164, v81
	ds_bpermute_b32 v116, v164, v86
	ds_bpermute_b32 v118, v164, v82
	ds_bpermute_b32 v117, v164, v87
	ds_bpermute_b32 v119, v164, v83
	s_waitcnt vmcnt(4) lgkmcnt(0)
	v_mov_b64_e32 v[90:91], v[196:197]
	v_mov_b64_e32 v[92:93], v[198:199]
	v_mov_b64_e32 v[102:103], v[200:201]
	v_mov_b64_e32 v[104:105], v[202:203]
	v_mov_b64_e32 v[106:107], v[204:205]
	v_mov_b64_e32 v[108:109], v[206:207]
	v_mov_b64_e32 v[110:111], v[208:209]
	v_mov_b64_e32 v[112:113], v[210:211]
	v_pk_mul_f32 v[96:97], v[102:103], v[94:95]
	v_pk_mul_f32 v[88:89], v[86:87], v[92:93]
	v_pk_mul_f32 v[92:93], v[84:85], v[90:91]
	v_pk_mul_f32 v[104:105], v[104:105], v[116:117]
	v_pk_mul_f32 v[90:91], v[106:107], v[114:115]
	v_pk_mul_f32 v[94:95], v[108:109], v[118:119]
	v_pk_mul_f32 v[102:103], v[82:83], v[112:113]
	v_pk_mul_f32 v[106:107], v[80:81], v[110:111]
	s_and_saveexec_b64 s[20:21], s[78:79]
	s_xor_b64 s[20:21], exec, s[20:21]
	v_pk_add_f32 v[86:87], v[88:89], v[104:105]
	v_pk_add_f32 v[84:85], v[92:93], v[96:97]
	v_pk_add_f32 v[82:83], v[102:103], v[94:95]
	v_pk_add_f32 v[80:81], v[106:107], v[90:91]
	s_andn2_saveexec_b64 s[20:21], s[20:21]
	v_sub_f32_e32 v87, v89, v105
	v_sub_f32_e32 v86, v88, v104
	v_sub_f32_e32 v85, v93, v97
	v_sub_f32_e32 v84, v92, v96
	v_sub_f32_e32 v83, v103, v95
	v_sub_f32_e32 v82, v102, v94
	v_sub_f32_e32 v81, v107, v91
	v_sub_f32_e32 v80, v106, v90
	s_or_b64 exec, exec, s[20:21]
.LBB0_1239:
	v_mov_b32_e32 v99, v98
	v_pk_mul_f32 v[84:85], v[98:99], v[84:85]
	v_pk_mul_f32 v[86:87], v[98:99], v[86:87]
	v_pk_mul_f32 v[80:81], v[98:99], v[80:81]
	v_cvt_pk_bf16_f32 v84, v84, v85
	v_cvt_pk_bf16_f32 v85, v86, v87
	v_cvt_pk_bf16_f32 v86, v80, v81
	v_pk_mul_f32 v[80:81], v[98:99], v[82:83]
	ds_read_b32 v99, v166 offset:192
	v_add3_u32 v98, s50, v167, 48
	v_cvt_pk_bf16_f32 v87, v80, v81
	v_lshlrev_b32_e32 v80, 4, v98
	v_and_b32_e32 v80, 0xfff0, v80
	s_and_b64 vcc, exec, s[70:71]
	v_lshlrev_b32_e32 v80, 2, v80
	global_store_dwordx4 v[100:101], v[84:87], off offset:256
	s_cbranch_vccnz .LBB0_1245
	v_mov_b32_e32 v81, v145
	v_lshl_add_u64 v[82:83], s[12:13], 0, v[80:81]
	v_mov_b32_e32 v141, v145
	v_lshl_add_u64 v[88:89], s[14:15], 0, v[80:81]
	v_lshl_add_u64 v[82:83], v[82:83], 0, v[140:141]
	v_lshl_add_u64 v[88:89], v[88:89], 0, v[140:141]
	ds_bpermute_b32 v88, v164, v76
	ds_bpermute_b32 v96, v164, v72
	ds_bpermute_b32 v89, v164, v77
	ds_bpermute_b32 v97, v164, v73
	ds_bpermute_b32 v94, v164, v78
	ds_bpermute_b32 v108, v164, v74
	ds_bpermute_b32 v95, v164, v79
	ds_bpermute_b32 v109, v164, v75
	s_waitcnt vmcnt(0) lgkmcnt(0)
	v_mov_b64_e32 v[84:85], v[212:213]
	v_mov_b64_e32 v[86:87], v[214:215]
	v_mov_b64_e32 v[90:91], v[216:217]
	v_mov_b64_e32 v[92:93], v[218:219]
	v_mov_b64_e32 v[100:101], v[220:221]
	v_mov_b64_e32 v[102:103], v[222:223]
	v_mov_b64_e32 v[104:105], v[224:225]
	v_mov_b64_e32 v[106:107], v[226:227]
	v_pk_mul_f32 v[90:91], v[90:91], v[88:89]
	v_pk_mul_f32 v[82:83], v[78:79], v[86:87]
	v_pk_mul_f32 v[86:87], v[76:77], v[84:85]
	v_pk_mul_f32 v[94:95], v[92:93], v[94:95]
	v_pk_mul_f32 v[84:85], v[100:101], v[96:97]
	v_pk_mul_f32 v[88:89], v[102:103], v[108:109]
	v_pk_mul_f32 v[92:93], v[74:75], v[106:107]
	v_pk_mul_f32 v[96:97], v[72:73], v[104:105]
	s_and_saveexec_b64 s[20:21], s[78:79]
	s_xor_b64 s[20:21], exec, s[20:21]
	v_pk_add_f32 v[78:79], v[82:83], v[94:95]
	v_pk_add_f32 v[76:77], v[86:87], v[90:91]
	v_pk_add_f32 v[74:75], v[92:93], v[88:89]
	v_pk_add_f32 v[72:73], v[96:97], v[84:85]
	s_andn2_saveexec_b64 s[20:21], s[20:21]
	v_sub_f32_e32 v79, v83, v95
	v_sub_f32_e32 v78, v82, v94
	v_sub_f32_e32 v77, v87, v91
	v_sub_f32_e32 v76, v86, v90
	v_sub_f32_e32 v75, v93, v89
	v_sub_f32_e32 v74, v92, v88
	v_sub_f32_e32 v73, v97, v85
	v_sub_f32_e32 v72, v96, v84
	s_or_b64 exec, exec, s[20:21]
; DI void rope_perm(f32x4& a0, f32x4& a1, int fq, int lane, const float* tcos, const float* tsin, int pos) {
;   f32x4 p0, p1;
; #pragma unroll
;   for (int e = 0; e < 4; ++e) { p0[e] = shx(a0[e], 32, lane); p1[e] = shx(a1[e], 32, lane); }
;   const int jb = 8 * (fq & 1);
;   const f32x4 c0 = *(const f32x4*)(tcos + pos * 16 + jb), c1 = *(const f32x4*)(tcos + pos * 16 + jb + 4);
;   const f32x4 s0 = *(const f32x4*)(tsin + pos * 16 + jb), s1 = *(const f32x4*)(tsin + pos * 16 + jb + 4);
;   if (fq < 2) { a0 = a0 * c0 - p0 * s0; a1 = a1 * c1 - p1 * s1; }
;   else        { a0 = a0 * c0 + p0 * s0; a1 = a1 * c1 + p1 * s1; }
; }
;   DI void operator()(const f32x4 (&acc)[2][2][4][2], const pg8::Unit& u, int wr, int wc, int fr_, int fq_) const {
;     ...
;             } else if (EPI == EPI_UQ) {
;               if (n == 0) {
;                 const float sc = rinv * (0.10206207261596575f * LOG2E);
;                 const int gb = u.pn * 256 + bj * 128 + wc * 32;
;                 const int hd = gb / 96; const int within = gb - hd * 96;
;                 f32x4 a0 = v, a1 = acc[ai][bj][m][1];
;                 if (within == 64) rope_perm(a0, a1, fq, t_ & 63, tcos, tsin, token & (S_ - 1));
;                 st_bf8((u16*)(big + E_QMLA) + (size_t)token * 768 + gb + 8 * fq, a0, a1, sc);
;               }
.LBB0_1245:
	s_waitcnt lgkmcnt(0)
	v_mul_f32_e32 v82, 0x3e16c740, v99
	v_mov_b64_e32 v[84:85], s[16:17]
	s_movk_i32 s20, 0x600
	v_mad_i64_i32 v[84:85], s[20:21], v98, s20, v[84:85]
	v_pk_mul_f32 v[76:77], v[82:83], v[76:77] op_sel_hi:[0,1]
	v_pk_mul_f32 v[78:79], v[82:83], v[78:79] op_sel_hi:[0,1]
	v_pk_mul_f32 v[72:73], v[82:83], v[72:73] op_sel_hi:[0,1]
	v_lshl_add_u64 v[84:85], s[18:19], 1, v[84:85]
	v_cvt_pk_bf16_f32 v76, v76, v77
	v_cvt_pk_bf16_f32 v77, v78, v79
	v_cvt_pk_bf16_f32 v78, v72, v73
	v_pk_mul_f32 v[72:73], v[82:83], v[74:75] op_sel_hi:[0,1]
	v_lshl_add_u64 v[84:85], v[84:85], 0, v[144:145]
	v_cvt_pk_bf16_f32 v79, v72, v73
	s_and_b64 vcc, exec, s[72:73]
	global_store_dwordx4 v[84:85], v[76:79], off
	s_cbranch_vccnz .LBB0_1251
	v_mov_b32_e32 v81, v145
	v_lshl_add_u64 v[72:73], s[12:13], 0, v[80:81]
	v_mov_b32_e32 v141, v145
	v_lshl_add_u64 v[78:79], s[14:15], 0, v[80:81]
	v_lshl_add_u64 v[72:73], v[72:73], 0, v[140:141]
	v_lshl_add_u64 v[78:79], v[78:79], 0, v[140:141]
	ds_bpermute_b32 v78, v164, v68
	ds_bpermute_b32 v98, v164, v64
	ds_bpermute_b32 v79, v164, v69
	ds_bpermute_b32 v99, v164, v65
	ds_bpermute_b32 v100, v164, v70
	ds_bpermute_b32 v102, v164, v66
	ds_bpermute_b32 v101, v164, v71
	ds_bpermute_b32 v103, v164, v67
	s_waitcnt vmcnt(0) lgkmcnt(0)
	v_mov_b64_e32 v[74:75], v[212:213]
	v_mov_b64_e32 v[76:77], v[214:215]
	v_mov_b64_e32 v[86:87], v[216:217]
	v_mov_b64_e32 v[88:89], v[218:219]
	v_mov_b64_e32 v[90:91], v[220:221]
	v_mov_b64_e32 v[92:93], v[222:223]
	v_mov_b64_e32 v[94:95], v[224:225]
	v_mov_b64_e32 v[96:97], v[226:227]
	v_pk_mul_f32 v[80:81], v[86:87], v[78:79]
	v_pk_mul_f32 v[72:73], v[70:71], v[76:77]
	v_pk_mul_f32 v[76:77], v[68:69], v[74:75]
	v_pk_mul_f32 v[88:89], v[88:89], v[100:101]
	v_pk_mul_f32 v[74:75], v[90:91], v[98:99]
	v_pk_mul_f32 v[78:79], v[92:93], v[102:103]
	v_pk_mul_f32 v[86:87], v[66:67], v[96:97]
	v_pk_mul_f32 v[90:91], v[64:65], v[94:95]
	s_and_saveexec_b64 s[20:21], s[78:79]
	s_xor_b64 s[20:21], exec, s[20:21]
	v_pk_add_f32 v[70:71], v[72:73], v[88:89]
	v_pk_add_f32 v[68:69], v[76:77], v[80:81]
	v_pk_add_f32 v[66:67], v[86:87], v[78:79]
	v_pk_add_f32 v[64:65], v[90:91], v[74:75]
	s_andn2_saveexec_b64 s[20:21], s[20:21]
	v_sub_f32_e32 v71, v73, v89
	v_sub_f32_e32 v70, v72, v88
	v_sub_f32_e32 v69, v77, v81
	v_sub_f32_e32 v68, v76, v80
	v_sub_f32_e32 v67, v87, v79
	v_sub_f32_e32 v66, v86, v78
	v_sub_f32_e32 v65, v91, v75
	v_sub_f32_e32 v64, v90, v74
	s_or_b64 exec, exec, s[20:21]
.LBB0_1251:
	v_mov_b32_e32 v83, v82
	v_pk_mul_f32 v[68:69], v[82:83], v[68:69]
	v_pk_mul_f32 v[70:71], v[82:83], v[70:71]
	v_pk_mul_f32 v[64:65], v[82:83], v[64:65]
	v_cvt_pk_bf16_f32 v68, v68, v69
	v_cvt_pk_bf16_f32 v69, v70, v71
	v_cvt_pk_bf16_f32 v70, v64, v65
	v_pk_mul_f32 v[64:65], v[82:83], v[66:67]
	ds_read_b32 v83, v166 offset:512
	v_add_u32_e32 v82, 0x80, v165
	v_cvt_pk_bf16_f32 v71, v64, v65
	v_lshlrev_b32_e32 v64, 4, v82
	v_and_b32_e32 v64, 0xfcf0, v64
	s_and_b64 vcc, exec, s[70:71]
	v_lshlrev_b32_e32 v64, 2, v64
	global_store_dwordx4 v[84:85], v[68:71], off offset:256
	s_cbranch_vccnz .LBB0_1257
	v_mov_b32_e32 v65, v145
	v_lshl_add_u64 v[66:67], s[12:13], 0, v[64:65]
	v_mov_b32_e32 v141, v145
	v_lshl_add_u64 v[72:73], s[14:15], 0, v[64:65]
	v_lshl_add_u64 v[66:67], v[66:67], 0, v[140:141]
	v_lshl_add_u64 v[72:73], v[72:73], 0, v[140:141]
	global_load_dwordx4 v[68:71], v[66:67], off
	global_load_dwordx4 v[74:77], v[72:73], off
	global_load_dwordx4 v[84:87], v[72:73], off offset:16
	global_load_dwordx4 v[88:91], v[66:67], off offset:16
	global_load_dwordx4 v[212:215], v[66:67], off offset:1024
	global_load_dwordx4 v[216:219], v[72:73], off offset:1024
	global_load_dwordx4 v[220:223], v[72:73], off offset:1040
	global_load_dwordx4 v[224:227], v[66:67], off offset:1040
	ds_bpermute_b32 v72, v164, v60
	ds_bpermute_b32 v80, v164, v56
	ds_bpermute_b32 v73, v164, v61
	ds_bpermute_b32 v81, v164, v57
	ds_bpermute_b32 v78, v164, v62
	ds_bpermute_b32 v92, v164, v58
	ds_bpermute_b32 v79, v164, v63
	ds_bpermute_b32 v93, v164, v59
	s_waitcnt vmcnt(4) lgkmcnt(0)
	v_pk_mul_f32 v[74:75], v[74:75], v[72:73]
	v_pk_mul_f32 v[66:67], v[62:63], v[70:71]
	v_pk_mul_f32 v[70:71], v[60:61], v[68:69]
	v_pk_mul_f32 v[78:79], v[76:77], v[78:79]
	v_pk_mul_f32 v[68:69], v[84:85], v[80:81]
	v_pk_mul_f32 v[72:73], v[86:87], v[92:93]
	v_pk_mul_f32 v[76:77], v[58:59], v[90:91]
	v_pk_mul_f32 v[80:81], v[56:57], v[88:89]
	s_and_saveexec_b64 s[20:21], s[78:79]
	s_xor_b64 s[20:21], exec, s[20:21]
	v_pk_add_f32 v[62:63], v[66:67], v[78:79]
	v_pk_add_f32 v[60:61], v[70:71], v[74:75]
	v_pk_add_f32 v[58:59], v[76:77], v[72:73]
	v_pk_add_f32 v[56:57], v[80:81], v[68:69]
	s_andn2_saveexec_b64 s[20:21], s[20:21]
	v_sub_f32_e32 v63, v67, v79
	v_sub_f32_e32 v62, v66, v78
	v_sub_f32_e32 v61, v71, v75
	v_sub_f32_e32 v60, v70, v74
	v_sub_f32_e32 v59, v77, v73
	v_sub_f32_e32 v58, v76, v72
	v_sub_f32_e32 v57, v81, v69
	v_sub_f32_e32 v56, v80, v68
	s_or_b64 exec, exec, s[20:21]
; DI void rope_perm(f32x4& a0, f32x4& a1, int fq, int lane, const float* tcos, const float* tsin, int pos) {
;   f32x4 p0, p1;
; #pragma unroll
;   for (int e = 0; e < 4; ++e) { p0[e] = shx(a0[e], 32, lane); p1[e] = shx(a1[e], 32, lane); }
;   const int jb = 8 * (fq & 1);
;   const f32x4 c0 = *(const f32x4*)(tcos + pos * 16 + jb), c1 = *(const f32x4*)(tcos + pos * 16 + jb + 4);
;   const f32x4 s0 = *(const f32x4*)(tsin + pos * 16 + jb), s1 = *(const f32x4*)(tsin + pos * 16 + jb + 4);
;   if (fq < 2) { a0 = a0 * c0 - p0 * s0; a1 = a1 * c1 - p1 * s1; }
;   else        { a0 = a0 * c0 + p0 * s0; a1 = a1 * c1 + p1 * s1; }
; }
;   DI void operator()(const f32x4 (&acc)[2][2][4][2], const pg8::Unit& u, int wr, int wc, int fr_, int fq_) const {
;     ...
;             } else if (EPI == EPI_UQ) {
;               if (n == 0) {
;                 const float sc = rinv * (0.10206207261596575f * LOG2E);
;                 const int gb = u.pn * 256 + bj * 128 + wc * 32;
;                 const int hd = gb / 96; const int within = gb - hd * 96;
;                 f32x4 a0 = v, a1 = acc[ai][bj][m][1];
;                 if (within == 64) rope_perm(a0, a1, fq, t_ & 63, tcos, tsin, token & (S_ - 1));
;                 st_bf8((u16*)(big + E_QMLA) + (size_t)token * 768 + gb + 8 * fq, a0, a1, sc);
;               }
.LBB0_1257:
	s_waitcnt lgkmcnt(0)
	v_mul_f32_e32 v66, 0x3e16c740, v83
	v_mov_b64_e32 v[68:69], s[16:17]
	s_movk_i32 s20, 0x600
	v_mad_i64_i32 v[68:69], s[20:21], v82, s20, v[68:69]
	v_pk_mul_f32 v[60:61], v[66:67], v[60:61] op_sel_hi:[0,1]
	v_pk_mul_f32 v[62:63], v[66:67], v[62:63] op_sel_hi:[0,1]
	v_pk_mul_f32 v[56:57], v[66:67], v[56:57] op_sel_hi:[0,1]
	v_lshl_add_u64 v[68:69], s[18:19], 1, v[68:69]
	v_cvt_pk_bf16_f32 v60, v60, v61
	v_cvt_pk_bf16_f32 v61, v62, v63
	v_cvt_pk_bf16_f32 v62, v56, v57
	v_pk_mul_f32 v[56:57], v[66:67], v[58:59] op_sel_hi:[0,1]
	v_lshl_add_u64 v[68:69], v[68:69], 0, v[144:145]
	v_cvt_pk_bf16_f32 v63, v56, v57
	s_and_b64 vcc, exec, s[72:73]
	global_store_dwordx4 v[68:69], v[60:63], off
	s_cbranch_vccnz .LBB0_1263
	v_mov_b32_e32 v65, v145
	v_lshl_add_u64 v[56:57], s[12:13], 0, v[64:65]
	v_mov_b32_e32 v141, v145
	v_lshl_add_u64 v[62:63], s[14:15], 0, v[64:65]
	v_lshl_add_u64 v[56:57], v[56:57], 0, v[140:141]
	v_lshl_add_u64 v[62:63], v[62:63], 0, v[140:141]
	global_load_dwordx4 v[58:61], v[56:57], off
	global_load_dwordx4 v[70:73], v[62:63], off
	global_load_dwordx4 v[74:77], v[62:63], off offset:16
	global_load_dwordx4 v[78:81], v[56:57], off offset:16
	global_load_dwordx4 v[212:215], v[56:57], off offset:1024
	global_load_dwordx4 v[216:219], v[62:63], off offset:1024
	global_load_dwordx4 v[220:223], v[62:63], off offset:1040
	global_load_dwordx4 v[224:227], v[56:57], off offset:1040
	ds_bpermute_b32 v62, v164, v52
	ds_bpermute_b32 v82, v164, v48
	ds_bpermute_b32 v63, v164, v53
	ds_bpermute_b32 v83, v164, v49
	ds_bpermute_b32 v84, v164, v54
	ds_bpermute_b32 v86, v164, v50
	ds_bpermute_b32 v85, v164, v55
	ds_bpermute_b32 v87, v164, v51
	s_waitcnt vmcnt(4) lgkmcnt(0)
	v_pk_mul_f32 v[64:65], v[70:71], v[62:63]
	v_pk_mul_f32 v[56:57], v[54:55], v[60:61]
	v_pk_mul_f32 v[60:61], v[52:53], v[58:59]
	v_pk_mul_f32 v[72:73], v[72:73], v[84:85]
	v_pk_mul_f32 v[58:59], v[74:75], v[82:83]
	v_pk_mul_f32 v[62:63], v[76:77], v[86:87]
	v_pk_mul_f32 v[70:71], v[50:51], v[80:81]
	v_pk_mul_f32 v[74:75], v[48:49], v[78:79]
	s_and_saveexec_b64 s[20:21], s[78:79]
	s_xor_b64 s[20:21], exec, s[20:21]
	v_pk_add_f32 v[54:55], v[56:57], v[72:73]
	v_pk_add_f32 v[52:53], v[60:61], v[64:65]
	v_pk_add_f32 v[50:51], v[70:71], v[62:63]
	v_pk_add_f32 v[48:49], v[74:75], v[58:59]
	s_andn2_saveexec_b64 s[20:21], s[20:21]
	v_sub_f32_e32 v55, v57, v73
	v_sub_f32_e32 v54, v56, v72
	v_sub_f32_e32 v53, v61, v65
	v_sub_f32_e32 v52, v60, v64
	v_sub_f32_e32 v51, v71, v63
	v_sub_f32_e32 v50, v70, v62
	v_sub_f32_e32 v49, v75, v59
	v_sub_f32_e32 v48, v74, v58
	s_or_b64 exec, exec, s[20:21]
.LBB0_1263:
	v_mov_b32_e32 v67, v66
	v_pk_mul_f32 v[52:53], v[66:67], v[52:53]
	v_pk_mul_f32 v[54:55], v[66:67], v[54:55]
	v_pk_mul_f32 v[48:49], v[66:67], v[48:49]
	v_cvt_pk_bf16_f32 v52, v52, v53
	v_cvt_pk_bf16_f32 v53, v54, v55
	v_cvt_pk_bf16_f32 v54, v48, v49
	v_pk_mul_f32 v[48:49], v[66:67], v[50:51]
	ds_read_b32 v67, v166 offset:576
	v_add_u32_e32 v66, 0x90, v165
	v_cvt_pk_bf16_f32 v55, v48, v49
	v_lshlrev_b32_e32 v48, 4, v66
	v_and_b32_e32 v48, 0xfdf0, v48
	s_and_b64 vcc, exec, s[70:71]
	v_lshlrev_b32_e32 v48, 2, v48
	global_store_dwordx4 v[68:69], v[52:55], off offset:256
	s_cbranch_vccnz .LBB0_1269
	v_mov_b32_e32 v49, v145
	v_lshl_add_u64 v[50:51], s[12:13], 0, v[48:49]
	v_mov_b32_e32 v141, v145
	v_lshl_add_u64 v[56:57], s[14:15], 0, v[48:49]
	v_lshl_add_u64 v[50:51], v[50:51], 0, v[140:141]
	v_lshl_add_u64 v[56:57], v[56:57], 0, v[140:141]
	global_load_dwordx4 v[196:199], v[50:51], off offset:1024
	global_load_dwordx4 v[200:203], v[56:57], off offset:1024
	global_load_dwordx4 v[204:207], v[56:57], off offset:1040
	global_load_dwordx4 v[208:211], v[50:51], off offset:1040
	ds_bpermute_b32 v56, v164, v44
	ds_bpermute_b32 v64, v164, v40
	ds_bpermute_b32 v57, v164, v45
	ds_bpermute_b32 v65, v164, v41
	ds_bpermute_b32 v62, v164, v46
	ds_bpermute_b32 v76, v164, v42
	ds_bpermute_b32 v63, v164, v47
	ds_bpermute_b32 v77, v164, v43
	s_waitcnt vmcnt(4) lgkmcnt(0)
	v_mov_b64_e32 v[52:53], v[212:213]
	v_mov_b64_e32 v[54:55], v[214:215]
	v_mov_b64_e32 v[58:59], v[216:217]
	v_mov_b64_e32 v[60:61], v[218:219]
	v_mov_b64_e32 v[68:69], v[220:221]
	v_mov_b64_e32 v[70:71], v[222:223]
	v_mov_b64_e32 v[72:73], v[224:225]
	v_mov_b64_e32 v[74:75], v[226:227]
	v_pk_mul_f32 v[58:59], v[58:59], v[56:57]
	v_pk_mul_f32 v[50:51], v[46:47], v[54:55]
	v_pk_mul_f32 v[54:55], v[44:45], v[52:53]
	v_pk_mul_f32 v[62:63], v[60:61], v[62:63]
	v_pk_mul_f32 v[52:53], v[68:69], v[64:65]
	v_pk_mul_f32 v[56:57], v[70:71], v[76:77]
	v_pk_mul_f32 v[60:61], v[42:43], v[74:75]
	v_pk_mul_f32 v[64:65], v[40:41], v[72:73]
	s_and_saveexec_b64 s[20:21], s[78:79]
	s_xor_b64 s[20:21], exec, s[20:21]
	v_pk_add_f32 v[46:47], v[50:51], v[62:63]
	v_pk_add_f32 v[44:45], v[54:55], v[58:59]
	v_pk_add_f32 v[42:43], v[60:61], v[56:57]
	v_pk_add_f32 v[40:41], v[64:65], v[52:53]
	s_andn2_saveexec_b64 s[20:21], s[20:21]
	v_sub_f32_e32 v47, v51, v63
	v_sub_f32_e32 v46, v50, v62
	v_sub_f32_e32 v45, v55, v59
	v_sub_f32_e32 v44, v54, v58
	v_sub_f32_e32 v43, v61, v57
	v_sub_f32_e32 v42, v60, v56
	v_sub_f32_e32 v41, v65, v53
	v_sub_f32_e32 v40, v64, v52
	s_or_b64 exec, exec, s[20:21]
; DI void rope_perm(f32x4& a0, f32x4& a1, int fq, int lane, const float* tcos, const float* tsin, int pos) {
;   f32x4 p0, p1;
; #pragma unroll
;   for (int e = 0; e < 4; ++e) { p0[e] = shx(a0[e], 32, lane); p1[e] = shx(a1[e], 32, lane); }
;   const int jb = 8 * (fq & 1);
;   const f32x4 c0 = *(const f32x4*)(tcos + pos * 16 + jb), c1 = *(const f32x4*)(tcos + pos * 16 + jb + 4);
;   const f32x4 s0 = *(const f32x4*)(tsin + pos * 16 + jb), s1 = *(const f32x4*)(tsin + pos * 16 + jb + 4);
;   if (fq < 2) { a0 = a0 * c0 - p0 * s0; a1 = a1 * c1 - p1 * s1; }
;   else        { a0 = a0 * c0 + p0 * s0; a1 = a1 * c1 + p1 * s1; }
; }
;   DI void operator()(const f32x4 (&acc)[2][2][4][2], const pg8::Unit& u, int wr, int wc, int fr_, int fq_) const {
;     ...
;             } else if (EPI == EPI_UQ) {
;               if (n == 0) {
;                 const float sc = rinv * (0.10206207261596575f * LOG2E);
;                 const int gb = u.pn * 256 + bj * 128 + wc * 32;
;                 const int hd = gb / 96; const int within = gb - hd * 96;
;                 f32x4 a0 = v, a1 = acc[ai][bj][m][1];
;                 if (within == 64) rope_perm(a0, a1, fq, t_ & 63, tcos, tsin, token & (S_ - 1));
;                 st_bf8((u16*)(big + E_QMLA) + (size_t)token * 768 + gb + 8 * fq, a0, a1, sc);
;               }
.LBB0_1269:
	s_waitcnt lgkmcnt(0)
	v_mul_f32_e32 v50, 0x3e16c740, v67
	v_mov_b64_e32 v[52:53], s[16:17]
	s_movk_i32 s20, 0x600
	v_mad_i64_i32 v[52:53], s[20:21], v66, s20, v[52:53]
	v_pk_mul_f32 v[44:45], v[50:51], v[44:45] op_sel_hi:[0,1]
	v_pk_mul_f32 v[46:47], v[50:51], v[46:47] op_sel_hi:[0,1]
	v_pk_mul_f32 v[40:41], v[50:51], v[40:41] op_sel_hi:[0,1]
	v_lshl_add_u64 v[52:53], s[18:19], 1, v[52:53]
	v_cvt_pk_bf16_f32 v44, v44, v45
	v_cvt_pk_bf16_f32 v45, v46, v47
	v_cvt_pk_bf16_f32 v46, v40, v41
	v_pk_mul_f32 v[40:41], v[50:51], v[42:43] op_sel_hi:[0,1]
	v_lshl_add_u64 v[52:53], v[52:53], 0, v[144:145]
	v_cvt_pk_bf16_f32 v47, v40, v41
	s_and_b64 vcc, exec, s[72:73]
	global_store_dwordx4 v[52:53], v[44:47], off
	s_cbranch_vccnz .LBB0_1275
	v_mov_b32_e32 v49, v145
	v_lshl_add_u64 v[40:41], s[12:13], 0, v[48:49]
	v_mov_b32_e32 v141, v145
	v_lshl_add_u64 v[46:47], s[14:15], 0, v[48:49]
	v_lshl_add_u64 v[40:41], v[40:41], 0, v[140:141]
	v_lshl_add_u64 v[46:47], v[46:47], 0, v[140:141]
	global_load_dwordx4 v[196:199], v[40:41], off offset:1024
	global_load_dwordx4 v[200:203], v[46:47], off offset:1024
	global_load_dwordx4 v[204:207], v[46:47], off offset:1040
	global_load_dwordx4 v[208:211], v[40:41], off offset:1040
	ds_bpermute_b32 v46, v164, v36
	ds_bpermute_b32 v66, v164, v32
	ds_bpermute_b32 v47, v164, v37
	ds_bpermute_b32 v67, v164, v33
	ds_bpermute_b32 v68, v164, v38
	ds_bpermute_b32 v70, v164, v34
	ds_bpermute_b32 v69, v164, v39
	ds_bpermute_b32 v71, v164, v35
	s_waitcnt vmcnt(4) lgkmcnt(0)
	v_mov_b64_e32 v[42:43], v[212:213]
	v_mov_b64_e32 v[44:45], v[214:215]
	v_mov_b64_e32 v[54:55], v[216:217]
	v_mov_b64_e32 v[56:57], v[218:219]
	v_mov_b64_e32 v[58:59], v[220:221]
	v_mov_b64_e32 v[60:61], v[222:223]
	v_mov_b64_e32 v[62:63], v[224:225]
	v_mov_b64_e32 v[64:65], v[226:227]
	v_pk_mul_f32 v[48:49], v[54:55], v[46:47]
	v_pk_mul_f32 v[40:41], v[38:39], v[44:45]
	v_pk_mul_f32 v[44:45], v[36:37], v[42:43]
	v_pk_mul_f32 v[56:57], v[56:57], v[68:69]
	v_pk_mul_f32 v[42:43], v[58:59], v[66:67]
	v_pk_mul_f32 v[46:47], v[60:61], v[70:71]
	v_pk_mul_f32 v[54:55], v[34:35], v[64:65]
	v_pk_mul_f32 v[58:59], v[32:33], v[62:63]
	s_and_saveexec_b64 s[20:21], s[78:79]
	s_xor_b64 s[20:21], exec, s[20:21]
	v_pk_add_f32 v[38:39], v[40:41], v[56:57]
	v_pk_add_f32 v[36:37], v[44:45], v[48:49]
	v_pk_add_f32 v[34:35], v[54:55], v[46:47]
	v_pk_add_f32 v[32:33], v[58:59], v[42:43]
	s_andn2_saveexec_b64 s[20:21], s[20:21]
	v_sub_f32_e32 v39, v41, v57
	v_sub_f32_e32 v38, v40, v56
	v_sub_f32_e32 v37, v45, v49
	v_sub_f32_e32 v36, v44, v48
	v_sub_f32_e32 v35, v55, v47
	v_sub_f32_e32 v34, v54, v46
	v_sub_f32_e32 v33, v59, v43
	v_sub_f32_e32 v32, v58, v42
	s_or_b64 exec, exec, s[20:21]
.LBB0_1275:
	v_mov_b32_e32 v51, v50
	v_pk_mul_f32 v[36:37], v[50:51], v[36:37]
	v_pk_mul_f32 v[38:39], v[50:51], v[38:39]
	v_pk_mul_f32 v[32:33], v[50:51], v[32:33]
	v_cvt_pk_bf16_f32 v36, v36, v37
	v_cvt_pk_bf16_f32 v37, v38, v39
	v_cvt_pk_bf16_f32 v38, v32, v33
	v_pk_mul_f32 v[32:33], v[50:51], v[34:35]
	ds_read_b32 v51, v166 offset:640
	v_add_u32_e32 v50, 0xa0, v165
	v_cvt_pk_bf16_f32 v39, v32, v33
	v_lshlrev_b32_e32 v32, 4, v50
	v_and_b32_e32 v32, 0xfef0, v32
	s_and_b64 vcc, exec, s[70:71]
	v_lshlrev_b32_e32 v32, 2, v32
	global_store_dwordx4 v[52:53], v[36:39], off offset:256
	s_cbranch_vccnz .LBB0_1281
	v_mov_b32_e32 v33, v145
	v_lshl_add_u64 v[34:35], s[12:13], 0, v[32:33]
	v_mov_b32_e32 v141, v145
	v_lshl_add_u64 v[40:41], s[14:15], 0, v[32:33]
	v_lshl_add_u64 v[34:35], v[34:35], 0, v[140:141]
	v_lshl_add_u64 v[40:41], v[40:41], 0, v[140:141]
	global_load_dwordx4 v[212:215], v[34:35], off offset:1024
	global_load_dwordx4 v[216:219], v[40:41], off offset:1024
	global_load_dwordx4 v[220:223], v[40:41], off offset:1040
	global_load_dwordx4 v[224:227], v[34:35], off offset:1040
	ds_bpermute_b32 v40, v164, v28
	ds_bpermute_b32 v48, v164, v24
	ds_bpermute_b32 v41, v164, v29
	ds_bpermute_b32 v49, v164, v25
	ds_bpermute_b32 v46, v164, v30
	ds_bpermute_b32 v60, v164, v26
	ds_bpermute_b32 v47, v164, v31
	ds_bpermute_b32 v61, v164, v27
	s_waitcnt vmcnt(4) lgkmcnt(0)
	v_mov_b64_e32 v[36:37], v[196:197]
	v_mov_b64_e32 v[38:39], v[198:199]
	v_mov_b64_e32 v[42:43], v[200:201]
	v_mov_b64_e32 v[44:45], v[202:203]
	v_mov_b64_e32 v[52:53], v[204:205]
	v_mov_b64_e32 v[54:55], v[206:207]
	v_mov_b64_e32 v[56:57], v[208:209]
	v_mov_b64_e32 v[58:59], v[210:211]
	v_pk_mul_f32 v[42:43], v[42:43], v[40:41]
	v_pk_mul_f32 v[34:35], v[30:31], v[38:39]
	v_pk_mul_f32 v[38:39], v[28:29], v[36:37]
	v_pk_mul_f32 v[46:47], v[44:45], v[46:47]
	v_pk_mul_f32 v[36:37], v[52:53], v[48:49]
	v_pk_mul_f32 v[40:41], v[54:55], v[60:61]
	v_pk_mul_f32 v[44:45], v[26:27], v[58:59]
	v_pk_mul_f32 v[48:49], v[24:25], v[56:57]
	s_and_saveexec_b64 s[20:21], s[78:79]
	s_xor_b64 s[20:21], exec, s[20:21]
	v_pk_add_f32 v[30:31], v[34:35], v[46:47]
	v_pk_add_f32 v[28:29], v[38:39], v[42:43]
	v_pk_add_f32 v[26:27], v[44:45], v[40:41]
	v_pk_add_f32 v[24:25], v[48:49], v[36:37]
	s_andn2_saveexec_b64 s[20:21], s[20:21]
	v_sub_f32_e32 v31, v35, v47
	v_sub_f32_e32 v30, v34, v46
	v_sub_f32_e32 v29, v39, v43
	v_sub_f32_e32 v28, v38, v42
	v_sub_f32_e32 v27, v45, v41
	v_sub_f32_e32 v26, v44, v40
	v_sub_f32_e32 v25, v49, v37
	v_sub_f32_e32 v24, v48, v36
	s_or_b64 exec, exec, s[20:21]
; DI void rope_perm(f32x4& a0, f32x4& a1, int fq, int lane, const float* tcos, const float* tsin, int pos) {
;   f32x4 p0, p1;
; #pragma unroll
;   for (int e = 0; e < 4; ++e) { p0[e] = shx(a0[e], 32, lane); p1[e] = shx(a1[e], 32, lane); }
;   const int jb = 8 * (fq & 1);
;   const f32x4 c0 = *(const f32x4*)(tcos + pos * 16 + jb), c1 = *(const f32x4*)(tcos + pos * 16 + jb + 4);
;   const f32x4 s0 = *(const f32x4*)(tsin + pos * 16 + jb), s1 = *(const f32x4*)(tsin + pos * 16 + jb + 4);
;   if (fq < 2) { a0 = a0 * c0 - p0 * s0; a1 = a1 * c1 - p1 * s1; }
;   else        { a0 = a0 * c0 + p0 * s0; a1 = a1 * c1 + p1 * s1; }
; }
;   DI void operator()(const f32x4 (&acc)[2][2][4][2], const pg8::Unit& u, int wr, int wc, int fr_, int fq_) const {
;     ...
;             } else if (EPI == EPI_UQ) {
;               if (n == 0) {
;                 const float sc = rinv * (0.10206207261596575f * LOG2E);
;                 const int gb = u.pn * 256 + bj * 128 + wc * 32;
;                 const int hd = gb / 96; const int within = gb - hd * 96;
;                 f32x4 a0 = v, a1 = acc[ai][bj][m][1];
;                 if (within == 64) rope_perm(a0, a1, fq, t_ & 63, tcos, tsin, token & (S_ - 1));
;                 st_bf8((u16*)(big + E_QMLA) + (size_t)token * 768 + gb + 8 * fq, a0, a1, sc);
;               }
.LBB0_1281:
	s_waitcnt lgkmcnt(0)
	v_mul_f32_e32 v34, 0x3e16c740, v51
	v_mov_b64_e32 v[36:37], s[16:17]
	s_movk_i32 s20, 0x600
	v_mad_i64_i32 v[36:37], s[20:21], v50, s20, v[36:37]
	v_pk_mul_f32 v[28:29], v[34:35], v[28:29] op_sel_hi:[0,1]
	v_pk_mul_f32 v[30:31], v[34:35], v[30:31] op_sel_hi:[0,1]
	v_pk_mul_f32 v[24:25], v[34:35], v[24:25] op_sel_hi:[0,1]
	v_lshl_add_u64 v[36:37], s[18:19], 1, v[36:37]
	v_cvt_pk_bf16_f32 v28, v28, v29
	v_cvt_pk_bf16_f32 v29, v30, v31
	v_cvt_pk_bf16_f32 v30, v24, v25
	v_pk_mul_f32 v[24:25], v[34:35], v[26:27] op_sel_hi:[0,1]
	v_lshl_add_u64 v[36:37], v[36:37], 0, v[144:145]
	v_cvt_pk_bf16_f32 v31, v24, v25
	s_and_b64 vcc, exec, s[72:73]
	global_store_dwordx4 v[36:37], v[28:31], off
	s_cbranch_vccnz .LBB0_1287
	v_mov_b32_e32 v33, v145
	v_lshl_add_u64 v[24:25], s[12:13], 0, v[32:33]
	v_mov_b32_e32 v141, v145
	v_lshl_add_u64 v[30:31], s[14:15], 0, v[32:33]
	v_lshl_add_u64 v[24:25], v[24:25], 0, v[140:141]
	v_lshl_add_u64 v[30:31], v[30:31], 0, v[140:141]
	global_load_dwordx4 v[212:215], v[24:25], off offset:1024
	global_load_dwordx4 v[216:219], v[30:31], off offset:1024
	global_load_dwordx4 v[220:223], v[30:31], off offset:1040
	global_load_dwordx4 v[224:227], v[24:25], off offset:1040
	ds_bpermute_b32 v30, v164, v20
	ds_bpermute_b32 v50, v164, v16
	ds_bpermute_b32 v31, v164, v21
	ds_bpermute_b32 v51, v164, v17
	ds_bpermute_b32 v52, v164, v22
	ds_bpermute_b32 v54, v164, v18
	ds_bpermute_b32 v53, v164, v23
	ds_bpermute_b32 v55, v164, v19
	s_waitcnt vmcnt(4) lgkmcnt(0)
	v_mov_b64_e32 v[26:27], v[196:197]
	v_mov_b64_e32 v[28:29], v[198:199]
	v_mov_b64_e32 v[38:39], v[200:201]
	v_mov_b64_e32 v[40:41], v[202:203]
	v_mov_b64_e32 v[42:43], v[204:205]
	v_mov_b64_e32 v[44:45], v[206:207]
	v_mov_b64_e32 v[46:47], v[208:209]
	v_mov_b64_e32 v[48:49], v[210:211]
	v_pk_mul_f32 v[32:33], v[38:39], v[30:31]
	v_pk_mul_f32 v[24:25], v[22:23], v[28:29]
	v_pk_mul_f32 v[28:29], v[20:21], v[26:27]
	v_pk_mul_f32 v[40:41], v[40:41], v[52:53]
	v_pk_mul_f32 v[26:27], v[42:43], v[50:51]
	v_pk_mul_f32 v[30:31], v[44:45], v[54:55]
	v_pk_mul_f32 v[38:39], v[18:19], v[48:49]
	v_pk_mul_f32 v[42:43], v[16:17], v[46:47]
	s_and_saveexec_b64 s[20:21], s[78:79]
	s_xor_b64 s[20:21], exec, s[20:21]
	v_pk_add_f32 v[22:23], v[24:25], v[40:41]
	v_pk_add_f32 v[20:21], v[28:29], v[32:33]
	v_pk_add_f32 v[18:19], v[38:39], v[30:31]
	v_pk_add_f32 v[16:17], v[42:43], v[26:27]
	s_andn2_saveexec_b64 s[20:21], s[20:21]
	v_sub_f32_e32 v23, v25, v41
	v_sub_f32_e32 v22, v24, v40
	v_sub_f32_e32 v21, v29, v33
	v_sub_f32_e32 v20, v28, v32
	v_sub_f32_e32 v19, v39, v31
	v_sub_f32_e32 v18, v38, v30
	v_sub_f32_e32 v17, v43, v27
	v_sub_f32_e32 v16, v42, v26
	s_or_b64 exec, exec, s[20:21]
.LBB0_1287:
	v_mov_b32_e32 v35, v34
	v_pk_mul_f32 v[20:21], v[34:35], v[20:21]
	v_pk_mul_f32 v[22:23], v[34:35], v[22:23]
	v_pk_mul_f32 v[16:17], v[34:35], v[16:17]
	v_cvt_pk_bf16_f32 v20, v20, v21
	v_cvt_pk_bf16_f32 v21, v22, v23
	v_cvt_pk_bf16_f32 v22, v16, v17
	v_pk_mul_f32 v[16:17], v[34:35], v[18:19]
	ds_read_b32 v35, v166 offset:704
	v_add_u32_e32 v34, 0xb0, v165
	v_cvt_pk_bf16_f32 v23, v16, v17
	v_lshlrev_b32_e32 v16, 4, v34
	v_and_b32_e32 v16, 0xfff0, v16
	s_and_b64 vcc, exec, s[70:71]
	v_lshlrev_b32_e32 v16, 2, v16
	global_store_dwordx4 v[36:37], v[20:23], off offset:256
	s_cbranch_vccnz .LBB0_1293
	v_mov_b32_e32 v17, v145
	v_lshl_add_u64 v[18:19], s[12:13], 0, v[16:17]
	v_mov_b32_e32 v141, v145
	v_lshl_add_u64 v[24:25], s[14:15], 0, v[16:17]
	v_lshl_add_u64 v[18:19], v[18:19], 0, v[140:141]
	v_lshl_add_u64 v[24:25], v[24:25], 0, v[140:141]
	ds_bpermute_b32 v24, v164, v12
	ds_bpermute_b32 v32, v164, v8
	ds_bpermute_b32 v25, v164, v13
	ds_bpermute_b32 v33, v164, v9
	ds_bpermute_b32 v30, v164, v14
	ds_bpermute_b32 v44, v164, v10
	ds_bpermute_b32 v31, v164, v15
	ds_bpermute_b32 v45, v164, v11
	s_waitcnt vmcnt(0) lgkmcnt(0)
	v_mov_b64_e32 v[20:21], v[212:213]
	v_mov_b64_e32 v[22:23], v[214:215]
	v_mov_b64_e32 v[26:27], v[216:217]
	v_mov_b64_e32 v[28:29], v[218:219]
	v_mov_b64_e32 v[36:37], v[220:221]
	v_mov_b64_e32 v[38:39], v[222:223]
	v_mov_b64_e32 v[40:41], v[224:225]
	v_mov_b64_e32 v[42:43], v[226:227]
	v_pk_mul_f32 v[26:27], v[26:27], v[24:25]
	v_pk_mul_f32 v[18:19], v[14:15], v[22:23]
	v_pk_mul_f32 v[22:23], v[12:13], v[20:21]
	v_pk_mul_f32 v[30:31], v[28:29], v[30:31]
	v_pk_mul_f32 v[20:21], v[36:37], v[32:33]
	v_pk_mul_f32 v[24:25], v[38:39], v[44:45]
	v_pk_mul_f32 v[28:29], v[10:11], v[42:43]
	v_pk_mul_f32 v[32:33], v[8:9], v[40:41]
	s_and_saveexec_b64 s[20:21], s[78:79]
	s_xor_b64 s[20:21], exec, s[20:21]
	v_pk_add_f32 v[14:15], v[18:19], v[30:31]
	v_pk_add_f32 v[12:13], v[22:23], v[26:27]
	v_pk_add_f32 v[10:11], v[28:29], v[24:25]
	v_pk_add_f32 v[8:9], v[32:33], v[20:21]
	s_andn2_saveexec_b64 s[20:21], s[20:21]
	v_sub_f32_e32 v15, v19, v31
	v_sub_f32_e32 v14, v18, v30
	v_sub_f32_e32 v13, v23, v27
	v_sub_f32_e32 v12, v22, v26
	v_sub_f32_e32 v11, v29, v25
	v_sub_f32_e32 v10, v28, v24
	v_sub_f32_e32 v9, v33, v21
	v_sub_f32_e32 v8, v32, v20
	s_or_b64 exec, exec, s[20:21]
